# GEMM K-loops: counted lgkmcnt waits at each fragment's first MFMA instead of a full wait before every cluster
# speedup vs baseline: 1.0097x; 1.0036x over previous
.LBB0_243:
	s_cmpk_eq_i32 s4, 0x700
	v_lshl_add_u64 v[170:171], v[152:153], 0, s[4:5]
	s_mov_b64 s[6:7], 0x4280100
	v_lshl_add_u64 v[170:171], v[170:171], 0, s[6:7]
	s_cselect_b64 vcc, -1, 0
	s_add_i32 s6, 0, 0x10000
	v_cndmask_b32_e32 v245, v171, v147, vcc
	v_add_u32_e32 v171, s6, v174
	ds_read_b128 v[176:179], v171
	ds_read_b128 v[180:183], v171 offset:1024
	ds_read_b128 v[184:187], v171 offset:2048
	ds_read_b128 v[188:191], v171 offset:3072
	v_cndmask_b32_e32 v244, v170, v146, vcc
	v_lshl_add_u64 v[170:171], v[168:169], 0, s[4:5]
	v_cndmask_b32_e32 v171, v171, v145, vcc
	v_cndmask_b32_e32 v170, v170, v144, vcc
	v_lshl_add_u64 v[228:229], v[148:149], 0, s[4:5]
	s_add_i32 m0, s26, 0xc000
	ds_read_b128 v[192:195], v175
	ds_read_b128 v[196:199], v175 offset:1024
	ds_read_b128 v[200:203], v175 offset:2048
	ds_read_b128 v[204:207], v175 offset:3072
	ds_read_b128 v[210:213], v175 offset:4096
	ds_read_b128 v[214:217], v175 offset:5120
	ds_read_b128 v[218:221], v175 offset:6144
	ds_read_b128 v[222:225], v175 offset:7168
	global_load_lds_dwordx4 v[228:229], off
	v_lshl_add_u64 v[228:229], v[150:151], 0, s[4:5]
	s_add_i32 m0, s26, 0xe000
	s_nop 0
	global_load_lds_dwordx4 v[228:229], off
	s_waitcnt lgkmcnt(8)
	s_barrier
	s_setprio 1
	s_waitcnt lgkmcnt(7)
	v_mfma_f32_16x16x32_bf16 v[126:129], v[176:179], v[192:195], v[126:129]
	v_mfma_f32_16x16x32_bf16 v[122:125], v[184:187], v[192:195], v[122:125]
	s_waitcnt lgkmcnt(5)
	v_mfma_f32_16x16x32_bf16 v[118:121], v[176:179], v[200:203], v[118:121]
	v_mfma_f32_16x16x32_bf16 v[114:117], v[184:187], v[200:203], v[114:117]
	s_waitcnt lgkmcnt(3)
	v_mfma_f32_16x16x32_bf16 v[110:113], v[176:179], v[210:213], v[110:113]
	v_mfma_f32_16x16x32_bf16 v[106:109], v[184:187], v[210:213], v[106:109]
	s_waitcnt lgkmcnt(1)
	v_mfma_f32_16x16x32_bf16 v[102:105], v[176:179], v[218:221], v[102:105]
	v_mfma_f32_16x16x32_bf16 v[98:101], v[184:187], v[218:221], v[98:101]
	v_mfma_f32_16x16x32_bf16 v[126:129], v[180:183], v[196:199], v[126:129]
	v_mfma_f32_16x16x32_bf16 v[122:125], v[188:191], v[196:199], v[122:125]
	v_mfma_f32_16x16x32_bf16 v[118:121], v[180:183], v[204:207], v[118:121]
	v_mfma_f32_16x16x32_bf16 v[114:117], v[188:191], v[204:207], v[114:117]
	v_mfma_f32_16x16x32_bf16 v[110:113], v[180:183], v[214:217], v[110:113]
	v_mfma_f32_16x16x32_bf16 v[106:109], v[188:191], v[214:217], v[106:109]
	s_waitcnt lgkmcnt(0)
	v_mfma_f32_16x16x32_bf16 v[102:105], v[180:183], v[222:225], v[102:105]
	v_mfma_f32_16x16x32_bf16 v[98:101], v[188:191], v[222:225], v[98:101]
	s_setprio 0
	s_barrier
	s_add_i32 s7, 0, 0x14000
	s_add_i32 s6, s6, s13
	v_add_u32_e32 v208, s7, v174
	v_lshl_add_u64 v[246:247], v[170:171], 0, v[132:133]
	s_mov_b32 m0, s6
	ds_read_b128 v[228:231], v208
	ds_read_b128 v[232:235], v208 offset:1024
	ds_read_b128 v[236:239], v208 offset:2048
	ds_read_b128 v[240:243], v208 offset:3072
	global_load_lds_dwordx4 v[246:247], off
	v_lshl_add_u64 v[248:249], v[170:171], 0, v[142:143]
	s_add_i32 m0, s6, 0x2000
	s_nop 0
	global_load_lds_dwordx4 v[248:249], off
	s_barrier
	s_setprio 1
	s_waitcnt lgkmcnt(3)
	v_mfma_f32_16x16x32_bf16 v[94:97], v[228:231], v[192:195], v[94:97]
	s_waitcnt lgkmcnt(1)
	v_mfma_f32_16x16x32_bf16 v[90:93], v[236:239], v[192:195], v[90:93]
	v_mfma_f32_16x16x32_bf16 v[86:89], v[228:231], v[200:203], v[86:89]
	v_mfma_f32_16x16x32_bf16 v[82:85], v[236:239], v[200:203], v[82:85]
	v_mfma_f32_16x16x32_bf16 v[78:81], v[228:231], v[210:213], v[78:81]
	v_mfma_f32_16x16x32_bf16 v[74:77], v[236:239], v[210:213], v[74:77]
	v_mfma_f32_16x16x32_bf16 v[70:73], v[228:231], v[218:221], v[70:73]
	v_mfma_f32_16x16x32_bf16 v[66:69], v[236:239], v[218:221], v[66:69]
	v_mfma_f32_16x16x32_bf16 v[94:97], v[232:235], v[196:199], v[94:97]
	s_waitcnt lgkmcnt(0)
	v_mfma_f32_16x16x32_bf16 v[90:93], v[240:243], v[196:199], v[90:93]
	v_mfma_f32_16x16x32_bf16 v[86:89], v[232:235], v[204:207], v[86:89]
	v_mfma_f32_16x16x32_bf16 v[82:85], v[240:243], v[204:207], v[82:85]
	v_mfma_f32_16x16x32_bf16 v[78:81], v[232:235], v[214:217], v[78:81]
	v_mfma_f32_16x16x32_bf16 v[74:77], v[240:243], v[214:217], v[74:77]
	v_mfma_f32_16x16x32_bf16 v[70:73], v[232:235], v[222:225], v[70:73]
	v_mfma_f32_16x16x32_bf16 v[66:69], v[240:243], v[222:225], v[66:69]
	s_setprio 0
	s_mov_b32 m0, s26
	v_lshl_add_u64 v[250:251], v[244:245], 0, v[132:133]
	s_barrier
	ds_read_b128 v[192:195], v175 offset:16384
	ds_read_b128 v[196:199], v175 offset:17408
	ds_read_b128 v[200:203], v175 offset:18432
	ds_read_b128 v[204:207], v175 offset:19456
	ds_read_b128 v[210:213], v175 offset:20480
	ds_read_b128 v[214:217], v175 offset:21504
	ds_read_b128 v[218:221], v175 offset:22528
	ds_read_b128 v[222:225], v175 offset:23552
	global_load_lds_dwordx4 v[250:251], off
	v_lshl_add_u64 v[252:253], v[244:245], 0, v[142:143]
	s_mov_b32 m0, s41
	s_nop 0
	global_load_lds_dwordx4 v[252:253], off
	s_barrier
	s_setprio 1
	s_waitcnt lgkmcnt(7)
	v_mfma_f32_16x16x32_bf16 v[62:65], v[176:179], v[192:195], v[62:65]
	v_mfma_f32_16x16x32_bf16 v[58:61], v[184:187], v[192:195], v[58:61]
	s_waitcnt lgkmcnt(5)
	v_mfma_f32_16x16x32_bf16 v[54:57], v[176:179], v[200:203], v[54:57]
	v_mfma_f32_16x16x32_bf16 v[50:53], v[184:187], v[200:203], v[50:53]
	s_waitcnt lgkmcnt(3)
	v_mfma_f32_16x16x32_bf16 v[46:49], v[176:179], v[210:213], v[46:49]
	v_mfma_f32_16x16x32_bf16 v[42:45], v[184:187], v[210:213], v[42:45]
	s_waitcnt lgkmcnt(1)
	v_mfma_f32_16x16x32_bf16 v[38:41], v[176:179], v[218:221], v[38:41]
	v_mfma_f32_16x16x32_bf16 v[34:37], v[184:187], v[218:221], v[34:37]
	v_mfma_f32_16x16x32_bf16 v[62:65], v[180:183], v[196:199], v[62:65]
	v_mfma_f32_16x16x32_bf16 v[58:61], v[188:191], v[196:199], v[58:61]
	v_mfma_f32_16x16x32_bf16 v[54:57], v[180:183], v[204:207], v[54:57]
	v_mfma_f32_16x16x32_bf16 v[50:53], v[188:191], v[204:207], v[50:53]
	v_mfma_f32_16x16x32_bf16 v[46:49], v[180:183], v[214:217], v[46:49]
	v_mfma_f32_16x16x32_bf16 v[42:45], v[188:191], v[214:217], v[42:45]
	s_waitcnt lgkmcnt(0)
	v_mfma_f32_16x16x32_bf16 v[38:41], v[180:183], v[222:225], v[38:41]
	v_mfma_f32_16x16x32_bf16 v[34:37], v[188:191], v[222:225], v[34:37]
	s_setprio 0
	s_barrier
	v_lshl_add_u64 v[176:177], v[170:171], 0, s[28:29]
	s_add_i32 s6, s7, s13
	v_lshl_add_u64 v[178:179], v[176:177], 0, v[132:133]
	s_mov_b32 m0, s6
	v_lshl_add_u64 v[176:177], v[176:177], 0, v[142:143]
	global_load_lds_dwordx4 v[178:179], off
	s_add_i32 m0, s6, 0x2000
	s_nop 0
	global_load_lds_dwordx4 v[176:177], off
	s_waitcnt vmcnt(6)
	s_barrier
	s_setprio 1
	v_mfma_f32_16x16x32_bf16 v[30:33], v[228:231], v[192:195], v[30:33]
	v_mfma_f32_16x16x32_bf16 v[26:29], v[236:239], v[192:195], v[26:29]
	v_mfma_f32_16x16x32_bf16 v[22:25], v[228:231], v[200:203], v[22:25]
	v_mfma_f32_16x16x32_bf16 v[18:21], v[236:239], v[200:203], v[18:21]
	v_mfma_f32_16x16x32_bf16 v[14:17], v[228:231], v[210:213], v[14:17]
	v_mfma_f32_16x16x32_bf16 v[10:13], v[236:239], v[210:213], v[10:13]
	v_mfma_f32_16x16x32_bf16 v[6:9], v[228:231], v[218:221], v[6:9]
	v_mfma_f32_16x16x32_bf16 v[2:5], v[236:239], v[218:221], v[2:5]
	v_mfma_f32_16x16x32_bf16 v[30:33], v[232:235], v[196:199], v[30:33]
	v_mfma_f32_16x16x32_bf16 v[26:29], v[240:243], v[196:199], v[26:29]
	v_mfma_f32_16x16x32_bf16 v[22:25], v[232:235], v[204:207], v[22:25]
	v_mfma_f32_16x16x32_bf16 v[18:21], v[240:243], v[204:207], v[18:21]
	v_mfma_f32_16x16x32_bf16 v[14:17], v[232:235], v[214:217], v[14:17]
	v_mfma_f32_16x16x32_bf16 v[10:13], v[240:243], v[214:217], v[10:13]
	v_mfma_f32_16x16x32_bf16 v[6:9], v[232:235], v[222:225], v[6:9]
	v_mfma_f32_16x16x32_bf16 v[2:5], v[240:243], v[222:225], v[2:5]
	s_setprio 0
	s_add_i32 s6, 0, 0x18000
	v_add_u32_e32 v188, s6, v174
	s_barrier
	ds_read_b128 v[176:179], v188
	ds_read_b128 v[180:183], v188 offset:1024
	ds_read_b128 v[184:187], v188 offset:2048
	ds_read_b128 v[188:191], v188 offset:3072
	v_lshl_add_u64 v[228:229], v[244:245], 0, s[28:29]
	s_mov_b32 m0, s42
	v_lshl_add_u64 v[230:231], v[228:229], 0, v[132:133]
	ds_read_b128 v[192:195], v175 offset:32768
	ds_read_b128 v[196:199], v175 offset:33792
	ds_read_b128 v[200:203], v175 offset:34816
	ds_read_b128 v[204:207], v175 offset:35840
	ds_read_b128 v[210:213], v175 offset:36864
	ds_read_b128 v[214:217], v175 offset:37888
	ds_read_b128 v[218:221], v175 offset:38912
	ds_read_b128 v[222:225], v175 offset:39936
	global_load_lds_dwordx4 v[230:231], off
	v_lshl_add_u64 v[228:229], v[228:229], 0, v[142:143]
	s_mov_b32 m0, s43
	s_nop 0
	global_load_lds_dwordx4 v[228:229], off
	s_waitcnt lgkmcnt(8)
	s_barrier
	s_setprio 1
	s_waitcnt lgkmcnt(7)
	v_mfma_f32_16x16x32_bf16 v[126:129], v[176:179], v[192:195], v[126:129]
	v_mfma_f32_16x16x32_bf16 v[122:125], v[184:187], v[192:195], v[122:125]
	s_waitcnt lgkmcnt(5)
	v_mfma_f32_16x16x32_bf16 v[118:121], v[176:179], v[200:203], v[118:121]
	v_mfma_f32_16x16x32_bf16 v[114:117], v[184:187], v[200:203], v[114:117]
	s_waitcnt lgkmcnt(3)
	v_mfma_f32_16x16x32_bf16 v[110:113], v[176:179], v[210:213], v[110:113]
	v_mfma_f32_16x16x32_bf16 v[106:109], v[184:187], v[210:213], v[106:109]
	s_waitcnt lgkmcnt(1)
	v_mfma_f32_16x16x32_bf16 v[102:105], v[176:179], v[218:221], v[102:105]
	v_mfma_f32_16x16x32_bf16 v[98:101], v[184:187], v[218:221], v[98:101]
	v_mfma_f32_16x16x32_bf16 v[126:129], v[180:183], v[196:199], v[126:129]
	v_mfma_f32_16x16x32_bf16 v[122:125], v[188:191], v[196:199], v[122:125]
	v_mfma_f32_16x16x32_bf16 v[118:121], v[180:183], v[204:207], v[118:121]
	v_mfma_f32_16x16x32_bf16 v[114:117], v[188:191], v[204:207], v[114:117]
	v_mfma_f32_16x16x32_bf16 v[110:113], v[180:183], v[214:217], v[110:113]
	v_mfma_f32_16x16x32_bf16 v[106:109], v[188:191], v[214:217], v[106:109]
	s_waitcnt lgkmcnt(0)
	v_mfma_f32_16x16x32_bf16 v[102:105], v[180:183], v[222:225], v[102:105]
	v_mfma_f32_16x16x32_bf16 v[98:101], v[188:191], v[222:225], v[98:101]
	s_setprio 0
	s_barrier
	s_add_i32 s7, 0, 0x1c000
	s_add_i32 s6, s6, s13
	v_add_u32_e32 v208, s7, v174
	v_lshl_add_u64 v[244:245], v[246:247], 0, s[30:31]
	s_mov_b32 m0, s6
	ds_read_b128 v[228:231], v208
	ds_read_b128 v[232:235], v208 offset:1024
	ds_read_b128 v[236:239], v208 offset:2048
	ds_read_b128 v[240:243], v208 offset:3072
	global_load_lds_dwordx4 v[244:245], off
	v_lshl_add_u64 v[244:245], v[248:249], 0, s[30:31]
	s_add_i32 m0, s6, 0x2000
	s_nop 0
	global_load_lds_dwordx4 v[244:245], off
	s_barrier
	s_setprio 1
	s_waitcnt lgkmcnt(3)
	v_mfma_f32_16x16x32_bf16 v[94:97], v[228:231], v[192:195], v[94:97]
	s_waitcnt lgkmcnt(1)
	v_mfma_f32_16x16x32_bf16 v[90:93], v[236:239], v[192:195], v[90:93]
	v_mfma_f32_16x16x32_bf16 v[86:89], v[228:231], v[200:203], v[86:89]
	v_mfma_f32_16x16x32_bf16 v[82:85], v[236:239], v[200:203], v[82:85]
	v_mfma_f32_16x16x32_bf16 v[78:81], v[228:231], v[210:213], v[78:81]
	v_mfma_f32_16x16x32_bf16 v[74:77], v[236:239], v[210:213], v[74:77]
	v_mfma_f32_16x16x32_bf16 v[70:73], v[228:231], v[218:221], v[70:73]
	v_mfma_f32_16x16x32_bf16 v[66:69], v[236:239], v[218:221], v[66:69]
	v_mfma_f32_16x16x32_bf16 v[94:97], v[232:235], v[196:199], v[94:97]
	s_waitcnt lgkmcnt(0)
	v_mfma_f32_16x16x32_bf16 v[90:93], v[240:243], v[196:199], v[90:93]
	v_mfma_f32_16x16x32_bf16 v[86:89], v[232:235], v[204:207], v[86:89]
	v_mfma_f32_16x16x32_bf16 v[82:85], v[240:243], v[204:207], v[82:85]
	v_mfma_f32_16x16x32_bf16 v[78:81], v[232:235], v[214:217], v[78:81]
	v_mfma_f32_16x16x32_bf16 v[74:77], v[240:243], v[214:217], v[74:77]
	v_mfma_f32_16x16x32_bf16 v[70:73], v[232:235], v[222:225], v[70:73]
	v_mfma_f32_16x16x32_bf16 v[66:69], v[240:243], v[222:225], v[66:69]
	s_setprio 0
	s_mov_b32 m0, s44
	v_lshl_add_u64 v[244:245], v[250:251], 0, s[30:31]
	s_barrier
	ds_read_b128 v[192:195], v175 offset:49152
	ds_read_b128 v[196:199], v175 offset:50176
	ds_read_b128 v[200:203], v175 offset:51200
	ds_read_b128 v[204:207], v175 offset:52224
	ds_read_b128 v[210:213], v175 offset:53248
	ds_read_b128 v[214:217], v175 offset:54272
	ds_read_b128 v[218:221], v175 offset:55296
	ds_read_b128 v[222:225], v175 offset:56320
	global_load_lds_dwordx4 v[244:245], off
	v_lshl_add_u64 v[244:245], v[252:253], 0, s[30:31]
	s_mov_b32 m0, s45
	s_nop 0
	global_load_lds_dwordx4 v[244:245], off
	s_barrier
	s_setprio 1
	s_waitcnt lgkmcnt(7)
	v_mfma_f32_16x16x32_bf16 v[62:65], v[176:179], v[192:195], v[62:65]
	v_mfma_f32_16x16x32_bf16 v[58:61], v[184:187], v[192:195], v[58:61]
	s_waitcnt lgkmcnt(5)
	v_mfma_f32_16x16x32_bf16 v[54:57], v[176:179], v[200:203], v[54:57]
	v_mfma_f32_16x16x32_bf16 v[50:53], v[184:187], v[200:203], v[50:53]
	s_waitcnt lgkmcnt(3)
	v_mfma_f32_16x16x32_bf16 v[46:49], v[176:179], v[210:213], v[46:49]
	v_mfma_f32_16x16x32_bf16 v[42:45], v[184:187], v[210:213], v[42:45]
	s_waitcnt lgkmcnt(1)
	v_mfma_f32_16x16x32_bf16 v[38:41], v[176:179], v[218:221], v[38:41]
	v_mfma_f32_16x16x32_bf16 v[34:37], v[184:187], v[218:221], v[34:37]
	v_mfma_f32_16x16x32_bf16 v[62:65], v[180:183], v[196:199], v[62:65]
	v_mfma_f32_16x16x32_bf16 v[58:61], v[188:191], v[196:199], v[58:61]
	v_mfma_f32_16x16x32_bf16 v[54:57], v[180:183], v[204:207], v[54:57]
	v_mfma_f32_16x16x32_bf16 v[50:53], v[188:191], v[204:207], v[50:53]
	v_mfma_f32_16x16x32_bf16 v[46:49], v[180:183], v[214:217], v[46:49]
	v_mfma_f32_16x16x32_bf16 v[42:45], v[188:191], v[214:217], v[42:45]
	s_waitcnt lgkmcnt(0)
	v_mfma_f32_16x16x32_bf16 v[38:41], v[180:183], v[222:225], v[38:41]
	v_mfma_f32_16x16x32_bf16 v[34:37], v[188:191], v[222:225], v[34:37]
	s_setprio 0
	s_barrier
	v_lshl_add_u64 v[170:171], v[170:171], 0, s[34:35]
	s_add_i32 s6, s7, s13
	v_lshl_add_u64 v[176:177], v[170:171], 0, v[132:133]
	s_mov_b32 m0, s6
	v_lshl_add_u64 v[170:171], v[170:171], 0, v[142:143]
	global_load_lds_dwordx4 v[176:177], off
	s_add_i32 m0, s6, 0x2000
	s_nop 0
	global_load_lds_dwordx4 v[170:171], off
	s_waitcnt vmcnt(6)
	s_barrier
	s_setprio 1
	v_mfma_f32_16x16x32_bf16 v[30:33], v[228:231], v[192:195], v[30:33]
	v_mfma_f32_16x16x32_bf16 v[26:29], v[236:239], v[192:195], v[26:29]
	v_mfma_f32_16x16x32_bf16 v[22:25], v[228:231], v[200:203], v[22:25]
	v_mfma_f32_16x16x32_bf16 v[18:21], v[236:239], v[200:203], v[18:21]
	v_mfma_f32_16x16x32_bf16 v[14:17], v[228:231], v[210:213], v[14:17]
	v_mfma_f32_16x16x32_bf16 v[10:13], v[236:239], v[210:213], v[10:13]
	v_mfma_f32_16x16x32_bf16 v[6:9], v[228:231], v[218:221], v[6:9]
	v_mfma_f32_16x16x32_bf16 v[2:5], v[236:239], v[218:221], v[2:5]
	v_mfma_f32_16x16x32_bf16 v[30:33], v[232:235], v[196:199], v[30:33]
	v_mfma_f32_16x16x32_bf16 v[26:29], v[240:243], v[196:199], v[26:29]
	v_mfma_f32_16x16x32_bf16 v[22:25], v[232:235], v[204:207], v[22:25]
	v_mfma_f32_16x16x32_bf16 v[18:21], v[240:243], v[204:207], v[18:21]
	v_mfma_f32_16x16x32_bf16 v[14:17], v[232:235], v[214:217], v[14:17]
	v_mfma_f32_16x16x32_bf16 v[10:13], v[240:243], v[214:217], v[10:13]
	v_mfma_f32_16x16x32_bf16 v[6:9], v[232:235], v[222:225], v[6:9]
	v_mfma_f32_16x16x32_bf16 v[2:5], v[240:243], v[222:225], v[2:5]
	s_setprio 0
	s_add_i32 s46, s46, 2
	s_add_u32 s4, s4, 0x100
	s_addc_u32 s5, s5, 0
	s_cmp_lt_u32 s46, 14
	s_barrier
	s_cbranch_scc1 .LBB0_243
	s_waitcnt vmcnt(0)
	s_cmpk_gt_u32 s12, 0xff
	s_cbranch_scc1 .LBB0_246
	s_barrier

.LBB0_756:
	s_add_u32 s42, s6, 0xfbd20080
	s_addc_u32 s43, s7, -1
	s_cmp_lg_u32 s41, 20
	s_cselect_b32 s43, s43, 0
	s_cselect_b32 s42, s42, 0
	s_add_i32 s44, 0, 0x10000
	v_add_u32_e32 v152, s44, v168
	ds_read_b128 v[170:173], v152
	ds_read_b128 v[174:177], v152 offset:1024
	ds_read_b128 v[178:181], v152 offset:2048
	ds_read_b128 v[182:185], v152 offset:3072
	v_lshl_add_u64 v[206:207], v[146:147], 0, s[42:43]
	v_lshl_add_u64 v[152:153], v[144:145], 0, s[42:43]
	v_lshl_add_u64 v[222:223], v[148:149], 0, s[6:7]
	s_add_i32 m0, s34, 0xc000
	ds_read_b128 v[186:189], v169
	ds_read_b128 v[190:193], v169 offset:1024
	ds_read_b128 v[194:197], v169 offset:2048
	ds_read_b128 v[198:201], v169 offset:3072
	ds_read_b128 v[202:205], v169 offset:4096
	ds_read_b128 v[210:213], v169 offset:5120
	ds_read_b128 v[214:217], v169 offset:6144
	ds_read_b128 v[218:221], v169 offset:7168
	global_load_lds_dwordx4 v[222:223], off
	v_lshl_add_u64 v[222:223], v[150:151], 0, s[6:7]
	s_add_i32 m0, s34, 0xe000
	s_nop 0
	global_load_lds_dwordx4 v[222:223], off
	s_waitcnt lgkmcnt(8)
	s_barrier
	s_setprio 1
	s_waitcnt lgkmcnt(7)
	v_mfma_f32_16x16x32_bf16 v[126:129], v[170:173], v[186:189], v[126:129]
	v_mfma_f32_16x16x32_bf16 v[122:125], v[178:181], v[186:189], v[122:125]
	s_waitcnt lgkmcnt(5)
	v_mfma_f32_16x16x32_bf16 v[118:121], v[170:173], v[194:197], v[118:121]
	v_mfma_f32_16x16x32_bf16 v[114:117], v[178:181], v[194:197], v[114:117]
	s_waitcnt lgkmcnt(3)
	v_mfma_f32_16x16x32_bf16 v[110:113], v[170:173], v[202:205], v[110:113]
	v_mfma_f32_16x16x32_bf16 v[106:109], v[178:181], v[202:205], v[106:109]
	s_waitcnt lgkmcnt(1)
	v_mfma_f32_16x16x32_bf16 v[102:105], v[170:173], v[214:217], v[102:105]
	v_mfma_f32_16x16x32_bf16 v[98:101], v[178:181], v[214:217], v[98:101]
	v_mfma_f32_16x16x32_bf16 v[126:129], v[174:177], v[190:193], v[126:129]
	v_mfma_f32_16x16x32_bf16 v[122:125], v[182:185], v[190:193], v[122:125]
	v_mfma_f32_16x16x32_bf16 v[118:121], v[174:177], v[198:201], v[118:121]
	v_mfma_f32_16x16x32_bf16 v[114:117], v[182:185], v[198:201], v[114:117]
	v_mfma_f32_16x16x32_bf16 v[110:113], v[174:177], v[210:213], v[110:113]
	v_mfma_f32_16x16x32_bf16 v[106:109], v[182:185], v[210:213], v[106:109]
	s_waitcnt lgkmcnt(0)
	v_mfma_f32_16x16x32_bf16 v[102:105], v[174:177], v[218:221], v[102:105]
	v_mfma_f32_16x16x32_bf16 v[98:101], v[182:185], v[218:221], v[98:101]
	s_setprio 0
	s_barrier
	s_add_i32 s42, 0, 0x14000
	s_add_i32 s43, s44, s33
	v_add_u32_e32 v208, s42, v168
	v_lshl_add_u64 v[240:241], v[152:153], 0, v[134:135]
	s_mov_b32 m0, s43
	ds_read_b128 v[222:225], v208
	ds_read_b128 v[228:231], v208 offset:1024
	ds_read_b128 v[232:235], v208 offset:2048
	ds_read_b128 v[236:239], v208 offset:3072
	global_load_lds_dwordx4 v[240:241], off
	v_lshl_add_u64 v[242:243], v[152:153], 0, v[142:143]
	s_add_i32 m0, s43, 0x2000
	s_nop 0
	global_load_lds_dwordx4 v[242:243], off
	s_barrier
	s_setprio 1
	s_waitcnt lgkmcnt(3)
	v_mfma_f32_16x16x32_bf16 v[94:97], v[222:225], v[186:189], v[94:97]
	s_waitcnt lgkmcnt(1)
	v_mfma_f32_16x16x32_bf16 v[90:93], v[232:235], v[186:189], v[90:93]
	v_mfma_f32_16x16x32_bf16 v[86:89], v[222:225], v[194:197], v[86:89]
	v_mfma_f32_16x16x32_bf16 v[82:85], v[232:235], v[194:197], v[82:85]
	v_mfma_f32_16x16x32_bf16 v[78:81], v[222:225], v[202:205], v[78:81]
	v_mfma_f32_16x16x32_bf16 v[74:77], v[232:235], v[202:205], v[74:77]
	v_mfma_f32_16x16x32_bf16 v[70:73], v[222:225], v[214:217], v[70:73]
	v_mfma_f32_16x16x32_bf16 v[66:69], v[232:235], v[214:217], v[66:69]
	v_mfma_f32_16x16x32_bf16 v[94:97], v[228:231], v[190:193], v[94:97]
	s_waitcnt lgkmcnt(0)
	v_mfma_f32_16x16x32_bf16 v[90:93], v[236:239], v[190:193], v[90:93]
	v_mfma_f32_16x16x32_bf16 v[86:89], v[228:231], v[198:201], v[86:89]
	v_mfma_f32_16x16x32_bf16 v[82:85], v[236:239], v[198:201], v[82:85]
	v_mfma_f32_16x16x32_bf16 v[78:81], v[228:231], v[210:213], v[78:81]
	v_mfma_f32_16x16x32_bf16 v[74:77], v[236:239], v[210:213], v[74:77]
	v_mfma_f32_16x16x32_bf16 v[70:73], v[228:231], v[218:221], v[70:73]
	v_mfma_f32_16x16x32_bf16 v[66:69], v[236:239], v[218:221], v[66:69]
	s_setprio 0
	s_mov_b32 m0, s34
	v_lshl_add_u64 v[244:245], v[206:207], 0, v[134:135]
	s_barrier
	ds_read_b128 v[186:189], v169 offset:16384
	ds_read_b128 v[190:193], v169 offset:17408
	ds_read_b128 v[194:197], v169 offset:18432
	ds_read_b128 v[198:201], v169 offset:19456
	ds_read_b128 v[202:205], v169 offset:20480
	ds_read_b128 v[210:213], v169 offset:21504
	ds_read_b128 v[214:217], v169 offset:22528
	ds_read_b128 v[218:221], v169 offset:23552
	global_load_lds_dwordx4 v[244:245], off
	v_lshl_add_u64 v[246:247], v[206:207], 0, v[142:143]
	s_mov_b32 m0, s35
	s_nop 0
	global_load_lds_dwordx4 v[246:247], off
	s_barrier
	s_setprio 1
	s_waitcnt lgkmcnt(7)
	v_mfma_f32_16x16x32_bf16 v[62:65], v[170:173], v[186:189], v[62:65]
	v_mfma_f32_16x16x32_bf16 v[58:61], v[178:181], v[186:189], v[58:61]
	s_waitcnt lgkmcnt(5)
	v_mfma_f32_16x16x32_bf16 v[54:57], v[170:173], v[194:197], v[54:57]
	v_mfma_f32_16x16x32_bf16 v[50:53], v[178:181], v[194:197], v[50:53]
	s_waitcnt lgkmcnt(3)
	v_mfma_f32_16x16x32_bf16 v[46:49], v[170:173], v[202:205], v[46:49]
	v_mfma_f32_16x16x32_bf16 v[42:45], v[178:181], v[202:205], v[42:45]
	s_waitcnt lgkmcnt(1)
	v_mfma_f32_16x16x32_bf16 v[38:41], v[170:173], v[214:217], v[38:41]
	v_mfma_f32_16x16x32_bf16 v[34:37], v[178:181], v[214:217], v[34:37]
	v_mfma_f32_16x16x32_bf16 v[62:65], v[174:177], v[190:193], v[62:65]
	v_mfma_f32_16x16x32_bf16 v[58:61], v[182:185], v[190:193], v[58:61]
	v_mfma_f32_16x16x32_bf16 v[54:57], v[174:177], v[198:201], v[54:57]
	v_mfma_f32_16x16x32_bf16 v[50:53], v[182:185], v[198:201], v[50:53]
	v_mfma_f32_16x16x32_bf16 v[46:49], v[174:177], v[210:213], v[46:49]
	v_mfma_f32_16x16x32_bf16 v[42:45], v[182:185], v[210:213], v[42:45]
	s_waitcnt lgkmcnt(0)
	v_mfma_f32_16x16x32_bf16 v[38:41], v[174:177], v[218:221], v[38:41]
	v_mfma_f32_16x16x32_bf16 v[34:37], v[182:185], v[218:221], v[34:37]
	s_setprio 0
	s_barrier
	v_lshl_add_u64 v[170:171], v[152:153], 0, s[14:15]
	s_add_i32 s42, s42, s33
	v_lshl_add_u64 v[172:173], v[170:171], 0, v[134:135]
	s_mov_b32 m0, s42
	v_lshl_add_u64 v[170:171], v[170:171], 0, v[142:143]
	global_load_lds_dwordx4 v[172:173], off
	s_add_i32 m0, s42, 0x2000
	s_nop 0
	global_load_lds_dwordx4 v[170:171], off
	s_waitcnt vmcnt(6)
	s_barrier
	s_setprio 1
	v_mfma_f32_16x16x32_bf16 v[30:33], v[222:225], v[186:189], v[30:33]
	v_mfma_f32_16x16x32_bf16 v[26:29], v[232:235], v[186:189], v[26:29]
	v_mfma_f32_16x16x32_bf16 v[22:25], v[222:225], v[194:197], v[22:25]
	v_mfma_f32_16x16x32_bf16 v[18:21], v[232:235], v[194:197], v[18:21]
	v_mfma_f32_16x16x32_bf16 v[14:17], v[222:225], v[202:205], v[14:17]
	v_mfma_f32_16x16x32_bf16 v[10:13], v[232:235], v[202:205], v[10:13]
	v_mfma_f32_16x16x32_bf16 v[6:9], v[222:225], v[214:217], v[6:9]
	v_mfma_f32_16x16x32_bf16 v[2:5], v[232:235], v[214:217], v[2:5]
	v_mfma_f32_16x16x32_bf16 v[30:33], v[228:231], v[190:193], v[30:33]
	v_mfma_f32_16x16x32_bf16 v[26:29], v[236:239], v[190:193], v[26:29]
	v_mfma_f32_16x16x32_bf16 v[22:25], v[228:231], v[198:201], v[22:25]
	v_mfma_f32_16x16x32_bf16 v[18:21], v[236:239], v[198:201], v[18:21]
	v_mfma_f32_16x16x32_bf16 v[14:17], v[228:231], v[210:213], v[14:17]
	v_mfma_f32_16x16x32_bf16 v[10:13], v[236:239], v[210:213], v[10:13]
	v_mfma_f32_16x16x32_bf16 v[6:9], v[228:231], v[218:221], v[6:9]
	v_mfma_f32_16x16x32_bf16 v[2:5], v[236:239], v[218:221], v[2:5]
	s_setprio 0
	s_add_i32 s42, 0, 0x18000
	v_add_u32_e32 v182, s42, v168
	s_barrier
	ds_read_b128 v[170:173], v182
	ds_read_b128 v[174:177], v182 offset:1024
	ds_read_b128 v[178:181], v182 offset:2048
	ds_read_b128 v[182:185], v182 offset:3072
	v_lshl_add_u64 v[206:207], v[206:207], 0, s[14:15]
	s_mov_b32 m0, s37
	v_lshl_add_u64 v[222:223], v[206:207], 0, v[134:135]
	ds_read_b128 v[186:189], v169 offset:32768
	ds_read_b128 v[190:193], v169 offset:33792
	ds_read_b128 v[194:197], v169 offset:34816
	ds_read_b128 v[198:201], v169 offset:35840
	ds_read_b128 v[202:205], v169 offset:36864
	ds_read_b128 v[210:213], v169 offset:37888
	ds_read_b128 v[214:217], v169 offset:38912
	ds_read_b128 v[218:221], v169 offset:39936
	global_load_lds_dwordx4 v[222:223], off
	v_lshl_add_u64 v[206:207], v[206:207], 0, v[142:143]
	s_mov_b32 m0, s38
	s_nop 0
	global_load_lds_dwordx4 v[206:207], off
	s_waitcnt lgkmcnt(8)
	s_barrier
	s_setprio 1
	s_waitcnt lgkmcnt(7)
	v_mfma_f32_16x16x32_bf16 v[126:129], v[170:173], v[186:189], v[126:129]
	v_mfma_f32_16x16x32_bf16 v[122:125], v[178:181], v[186:189], v[122:125]
	s_waitcnt lgkmcnt(5)
	v_mfma_f32_16x16x32_bf16 v[118:121], v[170:173], v[194:197], v[118:121]
	v_mfma_f32_16x16x32_bf16 v[114:117], v[178:181], v[194:197], v[114:117]
	s_waitcnt lgkmcnt(3)
	v_mfma_f32_16x16x32_bf16 v[110:113], v[170:173], v[202:205], v[110:113]
	v_mfma_f32_16x16x32_bf16 v[106:109], v[178:181], v[202:205], v[106:109]
	s_waitcnt lgkmcnt(1)
	v_mfma_f32_16x16x32_bf16 v[102:105], v[170:173], v[214:217], v[102:105]
	v_mfma_f32_16x16x32_bf16 v[98:101], v[178:181], v[214:217], v[98:101]
	v_mfma_f32_16x16x32_bf16 v[126:129], v[174:177], v[190:193], v[126:129]
	v_mfma_f32_16x16x32_bf16 v[122:125], v[182:185], v[190:193], v[122:125]
	v_mfma_f32_16x16x32_bf16 v[118:121], v[174:177], v[198:201], v[118:121]
	v_mfma_f32_16x16x32_bf16 v[114:117], v[182:185], v[198:201], v[114:117]
	v_mfma_f32_16x16x32_bf16 v[110:113], v[174:177], v[210:213], v[110:113]
	v_mfma_f32_16x16x32_bf16 v[106:109], v[182:185], v[210:213], v[106:109]
	s_waitcnt lgkmcnt(0)
	v_mfma_f32_16x16x32_bf16 v[102:105], v[174:177], v[218:221], v[102:105]
	v_mfma_f32_16x16x32_bf16 v[98:101], v[182:185], v[218:221], v[98:101]
	s_setprio 0
	s_barrier
	s_add_i32 s43, 0, 0x1c000
	v_add_u32_e32 v206, s43, v168
	s_add_i32 s42, s42, s33
	ds_read_b128 v[222:225], v206
	ds_read_b128 v[228:231], v206 offset:1024
	ds_read_b128 v[232:235], v206 offset:2048
	ds_read_b128 v[236:239], v206 offset:3072
	v_lshl_add_u64 v[206:207], v[240:241], 0, s[16:17]
	s_mov_b32 m0, s42
	s_nop 0
	global_load_lds_dwordx4 v[206:207], off
	v_lshl_add_u64 v[206:207], v[242:243], 0, s[16:17]
	s_add_i32 m0, s42, 0x2000
	s_nop 0
	global_load_lds_dwordx4 v[206:207], off
	s_barrier
	s_setprio 1
	s_waitcnt lgkmcnt(3)
	v_mfma_f32_16x16x32_bf16 v[94:97], v[222:225], v[186:189], v[94:97]
	s_waitcnt lgkmcnt(1)
	v_mfma_f32_16x16x32_bf16 v[90:93], v[232:235], v[186:189], v[90:93]
	v_mfma_f32_16x16x32_bf16 v[86:89], v[222:225], v[194:197], v[86:89]
	v_mfma_f32_16x16x32_bf16 v[82:85], v[232:235], v[194:197], v[82:85]
	v_mfma_f32_16x16x32_bf16 v[78:81], v[222:225], v[202:205], v[78:81]
	v_mfma_f32_16x16x32_bf16 v[74:77], v[232:235], v[202:205], v[74:77]
	v_mfma_f32_16x16x32_bf16 v[70:73], v[222:225], v[214:217], v[70:73]
	v_mfma_f32_16x16x32_bf16 v[66:69], v[232:235], v[214:217], v[66:69]
	v_mfma_f32_16x16x32_bf16 v[94:97], v[228:231], v[190:193], v[94:97]
	s_waitcnt lgkmcnt(0)
	v_mfma_f32_16x16x32_bf16 v[90:93], v[236:239], v[190:193], v[90:93]
	v_mfma_f32_16x16x32_bf16 v[86:89], v[228:231], v[198:201], v[86:89]
	v_mfma_f32_16x16x32_bf16 v[82:85], v[236:239], v[198:201], v[82:85]
	v_mfma_f32_16x16x32_bf16 v[78:81], v[228:231], v[210:213], v[78:81]
	v_mfma_f32_16x16x32_bf16 v[74:77], v[236:239], v[210:213], v[74:77]
	v_mfma_f32_16x16x32_bf16 v[70:73], v[228:231], v[218:221], v[70:73]
	v_mfma_f32_16x16x32_bf16 v[66:69], v[236:239], v[218:221], v[66:69]
	s_setprio 0
	s_mov_b32 m0, s39
	v_lshl_add_u64 v[206:207], v[244:245], 0, s[16:17]
	s_barrier
	ds_read_b128 v[186:189], v169 offset:49152
	ds_read_b128 v[190:193], v169 offset:50176
	ds_read_b128 v[194:197], v169 offset:51200
	ds_read_b128 v[198:201], v169 offset:52224
	ds_read_b128 v[202:205], v169 offset:53248
	ds_read_b128 v[210:213], v169 offset:54272
	ds_read_b128 v[214:217], v169 offset:55296
	ds_read_b128 v[218:221], v169 offset:56320
	global_load_lds_dwordx4 v[206:207], off
	v_lshl_add_u64 v[206:207], v[246:247], 0, s[16:17]
	s_mov_b32 m0, s40
	s_nop 0
	global_load_lds_dwordx4 v[206:207], off
	s_barrier
	s_setprio 1
	s_waitcnt lgkmcnt(7)
	v_mfma_f32_16x16x32_bf16 v[62:65], v[170:173], v[186:189], v[62:65]
	v_mfma_f32_16x16x32_bf16 v[58:61], v[178:181], v[186:189], v[58:61]
	s_waitcnt lgkmcnt(5)
	v_mfma_f32_16x16x32_bf16 v[54:57], v[170:173], v[194:197], v[54:57]
	v_mfma_f32_16x16x32_bf16 v[50:53], v[178:181], v[194:197], v[50:53]
	s_waitcnt lgkmcnt(3)
	v_mfma_f32_16x16x32_bf16 v[46:49], v[170:173], v[202:205], v[46:49]
	v_mfma_f32_16x16x32_bf16 v[42:45], v[178:181], v[202:205], v[42:45]
	s_waitcnt lgkmcnt(1)
	v_mfma_f32_16x16x32_bf16 v[38:41], v[170:173], v[214:217], v[38:41]
	v_mfma_f32_16x16x32_bf16 v[34:37], v[178:181], v[214:217], v[34:37]
	v_mfma_f32_16x16x32_bf16 v[62:65], v[174:177], v[190:193], v[62:65]
	v_mfma_f32_16x16x32_bf16 v[58:61], v[182:185], v[190:193], v[58:61]
	v_mfma_f32_16x16x32_bf16 v[54:57], v[174:177], v[198:201], v[54:57]
	v_mfma_f32_16x16x32_bf16 v[50:53], v[182:185], v[198:201], v[50:53]
	v_mfma_f32_16x16x32_bf16 v[46:49], v[174:177], v[210:213], v[46:49]
	v_mfma_f32_16x16x32_bf16 v[42:45], v[182:185], v[210:213], v[42:45]
	s_waitcnt lgkmcnt(0)
	v_mfma_f32_16x16x32_bf16 v[38:41], v[174:177], v[218:221], v[38:41]
	v_mfma_f32_16x16x32_bf16 v[34:37], v[182:185], v[218:221], v[34:37]
	s_setprio 0
	s_barrier
	v_lshl_add_u64 v[152:153], v[152:153], 0, s[18:19]
	s_add_i32 s42, s43, s33
	v_lshl_add_u64 v[170:171], v[152:153], 0, v[134:135]
	s_mov_b32 m0, s42
	v_lshl_add_u64 v[152:153], v[152:153], 0, v[142:143]
	global_load_lds_dwordx4 v[170:171], off
	s_add_i32 m0, s42, 0x2000
	s_nop 0
	global_load_lds_dwordx4 v[152:153], off
	s_waitcnt vmcnt(6)
	s_barrier
	s_setprio 1
	v_mfma_f32_16x16x32_bf16 v[30:33], v[222:225], v[186:189], v[30:33]
	v_mfma_f32_16x16x32_bf16 v[26:29], v[232:235], v[186:189], v[26:29]
	v_mfma_f32_16x16x32_bf16 v[22:25], v[222:225], v[194:197], v[22:25]
	v_mfma_f32_16x16x32_bf16 v[18:21], v[232:235], v[194:197], v[18:21]
	v_mfma_f32_16x16x32_bf16 v[14:17], v[222:225], v[202:205], v[14:17]
	v_mfma_f32_16x16x32_bf16 v[10:13], v[232:235], v[202:205], v[10:13]
	v_mfma_f32_16x16x32_bf16 v[6:9], v[222:225], v[214:217], v[6:9]
	v_mfma_f32_16x16x32_bf16 v[2:5], v[232:235], v[214:217], v[2:5]
	v_mfma_f32_16x16x32_bf16 v[30:33], v[228:231], v[190:193], v[30:33]
	v_mfma_f32_16x16x32_bf16 v[26:29], v[236:239], v[190:193], v[26:29]
	v_mfma_f32_16x16x32_bf16 v[22:25], v[228:231], v[198:201], v[22:25]
	v_mfma_f32_16x16x32_bf16 v[18:21], v[236:239], v[198:201], v[18:21]
	v_mfma_f32_16x16x32_bf16 v[14:17], v[228:231], v[210:213], v[14:17]
	v_mfma_f32_16x16x32_bf16 v[10:13], v[236:239], v[210:213], v[10:13]
	v_mfma_f32_16x16x32_bf16 v[6:9], v[228:231], v[218:221], v[6:9]
	v_mfma_f32_16x16x32_bf16 v[2:5], v[236:239], v[218:221], v[2:5]
	s_setprio 0
	s_add_i32 s41, s41, 2
	s_add_u32 s6, s6, 0x100
	s_addc_u32 s7, s7, 0
	s_cmp_lt_u32 s41, 22
	s_barrier
	s_cbranch_scc1 .LBB0_756
	s_waitcnt vmcnt(0)
	s_cmpk_gt_u32 s31, 0xff
	s_cbranch_scc1 .LBB0_759
	s_barrier

.LBB0_914:
	s_cmpk_eq_i32 s6, 0x700
	v_lshl_add_u64 v[170:171], v[150:151], 0, s[6:7]
	v_lshl_add_u64 v[170:171], v[170:171], 0, s[20:21]
	s_cselect_b64 vcc, -1, 0
	s_add_i32 s9, 0, 0x10000
	v_cndmask_b32_e32 v245, v171, v149, vcc
	v_add_u32_e32 v171, s9, v173
	ds_read_b128 v[176:179], v171
	ds_read_b128 v[180:183], v171 offset:1024
	ds_read_b128 v[184:187], v171 offset:2048
	ds_read_b128 v[188:191], v171 offset:3072
	v_cndmask_b32_e32 v244, v170, v148, vcc
	v_lshl_add_u64 v[170:171], v[168:169], 0, s[6:7]
	v_cndmask_b32_e32 v171, v171, v147, vcc
	v_cndmask_b32_e32 v170, v170, v146, vcc
	v_lshl_add_u64 v[228:229], v[152:153], 0, s[6:7]
	s_add_i32 m0, s34, 0xc000
	ds_read_b128 v[192:195], v174
	ds_read_b128 v[196:199], v174 offset:1024
	ds_read_b128 v[200:203], v174 offset:2048
	ds_read_b128 v[204:207], v174 offset:3072
	ds_read_b128 v[210:213], v174 offset:4096
	ds_read_b128 v[214:217], v174 offset:5120
	ds_read_b128 v[218:221], v174 offset:6144
	ds_read_b128 v[222:225], v174 offset:7168
	global_load_lds_dwordx4 v[228:229], off
	v_lshl_add_u64 v[228:229], v[166:167], 0, s[6:7]
	s_add_i32 m0, s34, 0xe000
	s_nop 0
	global_load_lds_dwordx4 v[228:229], off
	s_waitcnt lgkmcnt(8)
	s_barrier
	s_setprio 1
	s_waitcnt lgkmcnt(7)
	v_mfma_f32_16x16x32_bf16 v[126:129], v[176:179], v[192:195], v[126:129]
	v_mfma_f32_16x16x32_bf16 v[122:125], v[184:187], v[192:195], v[122:125]
	s_waitcnt lgkmcnt(5)
	v_mfma_f32_16x16x32_bf16 v[118:121], v[176:179], v[200:203], v[118:121]
	v_mfma_f32_16x16x32_bf16 v[114:117], v[184:187], v[200:203], v[114:117]
	s_waitcnt lgkmcnt(3)
	v_mfma_f32_16x16x32_bf16 v[110:113], v[176:179], v[210:213], v[110:113]
	v_mfma_f32_16x16x32_bf16 v[106:109], v[184:187], v[210:213], v[106:109]
	s_waitcnt lgkmcnt(1)
	v_mfma_f32_16x16x32_bf16 v[102:105], v[176:179], v[218:221], v[102:105]
	v_mfma_f32_16x16x32_bf16 v[98:101], v[184:187], v[218:221], v[98:101]
	v_mfma_f32_16x16x32_bf16 v[126:129], v[180:183], v[196:199], v[126:129]
	v_mfma_f32_16x16x32_bf16 v[122:125], v[188:191], v[196:199], v[122:125]
	v_mfma_f32_16x16x32_bf16 v[118:121], v[180:183], v[204:207], v[118:121]
	v_mfma_f32_16x16x32_bf16 v[114:117], v[188:191], v[204:207], v[114:117]
	v_mfma_f32_16x16x32_bf16 v[110:113], v[180:183], v[214:217], v[110:113]
	v_mfma_f32_16x16x32_bf16 v[106:109], v[188:191], v[214:217], v[106:109]
	s_waitcnt lgkmcnt(0)
	v_mfma_f32_16x16x32_bf16 v[102:105], v[180:183], v[222:225], v[102:105]
	v_mfma_f32_16x16x32_bf16 v[98:101], v[188:191], v[222:225], v[98:101]
	s_setprio 0
	s_barrier
	s_add_i32 s57, 0, 0x14000
	s_add_i32 s9, s9, s39
	v_add_u32_e32 v175, s57, v173
	v_lshl_add_u64 v[246:247], v[170:171], 0, v[134:135]
	s_mov_b32 m0, s9
	ds_read_b128 v[228:231], v175
	ds_read_b128 v[232:235], v175 offset:1024
	ds_read_b128 v[236:239], v175 offset:2048
	ds_read_b128 v[240:243], v175 offset:3072
	global_load_lds_dwordx4 v[246:247], off
	v_lshl_add_u64 v[248:249], v[170:171], 0, v[144:145]
	s_add_i32 m0, s9, 0x2000
	s_nop 0
	global_load_lds_dwordx4 v[248:249], off
	s_barrier
	s_setprio 1
	s_waitcnt lgkmcnt(3)
	v_mfma_f32_16x16x32_bf16 v[94:97], v[228:231], v[192:195], v[94:97]
	s_waitcnt lgkmcnt(1)
	v_mfma_f32_16x16x32_bf16 v[90:93], v[236:239], v[192:195], v[90:93]
	v_mfma_f32_16x16x32_bf16 v[86:89], v[228:231], v[200:203], v[86:89]
	v_mfma_f32_16x16x32_bf16 v[82:85], v[236:239], v[200:203], v[82:85]
	v_mfma_f32_16x16x32_bf16 v[78:81], v[228:231], v[210:213], v[78:81]
	v_mfma_f32_16x16x32_bf16 v[74:77], v[236:239], v[210:213], v[74:77]
	v_mfma_f32_16x16x32_bf16 v[70:73], v[228:231], v[218:221], v[70:73]
	v_mfma_f32_16x16x32_bf16 v[66:69], v[236:239], v[218:221], v[66:69]
	v_mfma_f32_16x16x32_bf16 v[94:97], v[232:235], v[196:199], v[94:97]
	s_waitcnt lgkmcnt(0)
	v_mfma_f32_16x16x32_bf16 v[90:93], v[240:243], v[196:199], v[90:93]
	v_mfma_f32_16x16x32_bf16 v[86:89], v[232:235], v[204:207], v[86:89]
	v_mfma_f32_16x16x32_bf16 v[82:85], v[240:243], v[204:207], v[82:85]
	v_mfma_f32_16x16x32_bf16 v[78:81], v[232:235], v[214:217], v[78:81]
	v_mfma_f32_16x16x32_bf16 v[74:77], v[240:243], v[214:217], v[74:77]
	v_mfma_f32_16x16x32_bf16 v[70:73], v[232:235], v[222:225], v[70:73]
	v_mfma_f32_16x16x32_bf16 v[66:69], v[240:243], v[222:225], v[66:69]
	s_setprio 0
	s_mov_b32 m0, s34
	v_lshl_add_u64 v[250:251], v[244:245], 0, v[134:135]
	s_barrier
	ds_read_b128 v[192:195], v174 offset:16384
	ds_read_b128 v[196:199], v174 offset:17408
	ds_read_b128 v[200:203], v174 offset:18432
	ds_read_b128 v[204:207], v174 offset:19456
	ds_read_b128 v[210:213], v174 offset:20480
	ds_read_b128 v[214:217], v174 offset:21504
	ds_read_b128 v[218:221], v174 offset:22528
	ds_read_b128 v[222:225], v174 offset:23552
	global_load_lds_dwordx4 v[250:251], off
	v_lshl_add_u64 v[252:253], v[244:245], 0, v[144:145]
	s_mov_b32 m0, s41
	s_nop 0
	global_load_lds_dwordx4 v[252:253], off
	s_barrier
	s_setprio 1
	s_waitcnt lgkmcnt(7)
	v_mfma_f32_16x16x32_bf16 v[62:65], v[176:179], v[192:195], v[62:65]
	v_mfma_f32_16x16x32_bf16 v[58:61], v[184:187], v[192:195], v[58:61]
	s_waitcnt lgkmcnt(5)
	v_mfma_f32_16x16x32_bf16 v[54:57], v[176:179], v[200:203], v[54:57]
	v_mfma_f32_16x16x32_bf16 v[50:53], v[184:187], v[200:203], v[50:53]
	s_waitcnt lgkmcnt(3)
	v_mfma_f32_16x16x32_bf16 v[46:49], v[176:179], v[210:213], v[46:49]
	v_mfma_f32_16x16x32_bf16 v[42:45], v[184:187], v[210:213], v[42:45]
	s_waitcnt lgkmcnt(1)
	v_mfma_f32_16x16x32_bf16 v[38:41], v[176:179], v[218:221], v[38:41]
	v_mfma_f32_16x16x32_bf16 v[34:37], v[184:187], v[218:221], v[34:37]
	v_mfma_f32_16x16x32_bf16 v[62:65], v[180:183], v[196:199], v[62:65]
	v_mfma_f32_16x16x32_bf16 v[58:61], v[188:191], v[196:199], v[58:61]
	v_mfma_f32_16x16x32_bf16 v[54:57], v[180:183], v[204:207], v[54:57]
	v_mfma_f32_16x16x32_bf16 v[50:53], v[188:191], v[204:207], v[50:53]
	v_mfma_f32_16x16x32_bf16 v[46:49], v[180:183], v[214:217], v[46:49]
	v_mfma_f32_16x16x32_bf16 v[42:45], v[188:191], v[214:217], v[42:45]
	s_waitcnt lgkmcnt(0)
	v_mfma_f32_16x16x32_bf16 v[38:41], v[180:183], v[222:225], v[38:41]
	v_mfma_f32_16x16x32_bf16 v[34:37], v[188:191], v[222:225], v[34:37]
	s_setprio 0
	s_barrier
	v_lshl_add_u64 v[176:177], v[170:171], 0, s[10:11]
	s_add_i32 s9, s57, s39
	v_lshl_add_u64 v[178:179], v[176:177], 0, v[134:135]
	s_mov_b32 m0, s9
	v_lshl_add_u64 v[176:177], v[176:177], 0, v[144:145]
	global_load_lds_dwordx4 v[178:179], off
	s_add_i32 m0, s9, 0x2000
	s_nop 0
	global_load_lds_dwordx4 v[176:177], off
	s_waitcnt vmcnt(6)
	s_barrier
	s_setprio 1
	v_mfma_f32_16x16x32_bf16 v[30:33], v[228:231], v[192:195], v[30:33]
	v_mfma_f32_16x16x32_bf16 v[26:29], v[236:239], v[192:195], v[26:29]
	v_mfma_f32_16x16x32_bf16 v[22:25], v[228:231], v[200:203], v[22:25]
	v_mfma_f32_16x16x32_bf16 v[18:21], v[236:239], v[200:203], v[18:21]
	v_mfma_f32_16x16x32_bf16 v[14:17], v[228:231], v[210:213], v[14:17]
	v_mfma_f32_16x16x32_bf16 v[10:13], v[236:239], v[210:213], v[10:13]
	v_mfma_f32_16x16x32_bf16 v[6:9], v[228:231], v[218:221], v[6:9]
	v_mfma_f32_16x16x32_bf16 v[2:5], v[236:239], v[218:221], v[2:5]
	v_mfma_f32_16x16x32_bf16 v[30:33], v[232:235], v[196:199], v[30:33]
	v_mfma_f32_16x16x32_bf16 v[26:29], v[240:243], v[196:199], v[26:29]
	v_mfma_f32_16x16x32_bf16 v[22:25], v[232:235], v[204:207], v[22:25]
	v_mfma_f32_16x16x32_bf16 v[18:21], v[240:243], v[204:207], v[18:21]
	v_mfma_f32_16x16x32_bf16 v[14:17], v[232:235], v[214:217], v[14:17]
	v_mfma_f32_16x16x32_bf16 v[10:13], v[240:243], v[214:217], v[10:13]
	v_mfma_f32_16x16x32_bf16 v[6:9], v[232:235], v[222:225], v[6:9]
	v_mfma_f32_16x16x32_bf16 v[2:5], v[240:243], v[222:225], v[2:5]
	s_setprio 0
	s_add_i32 s9, 0, 0x18000
	v_add_u32_e32 v175, s9, v173
	s_barrier
	ds_read_b128 v[176:179], v175
	ds_read_b128 v[180:183], v175 offset:1024
	ds_read_b128 v[184:187], v175 offset:2048
	ds_read_b128 v[188:191], v175 offset:3072
	v_lshl_add_u64 v[228:229], v[244:245], 0, s[10:11]
	s_mov_b32 m0, s42
	v_lshl_add_u64 v[230:231], v[228:229], 0, v[134:135]
	ds_read_b128 v[192:195], v174 offset:32768
	ds_read_b128 v[196:199], v174 offset:33792
	ds_read_b128 v[200:203], v174 offset:34816
	ds_read_b128 v[204:207], v174 offset:35840
	ds_read_b128 v[210:213], v174 offset:36864
	ds_read_b128 v[214:217], v174 offset:37888
	ds_read_b128 v[218:221], v174 offset:38912
	ds_read_b128 v[222:225], v174 offset:39936
	global_load_lds_dwordx4 v[230:231], off
	v_lshl_add_u64 v[228:229], v[228:229], 0, v[144:145]
	s_mov_b32 m0, s43
	s_nop 0
	global_load_lds_dwordx4 v[228:229], off
	s_waitcnt lgkmcnt(8)
	s_barrier
	s_setprio 1
	s_waitcnt lgkmcnt(7)
	v_mfma_f32_16x16x32_bf16 v[126:129], v[176:179], v[192:195], v[126:129]
	v_mfma_f32_16x16x32_bf16 v[122:125], v[184:187], v[192:195], v[122:125]
	s_waitcnt lgkmcnt(5)
	v_mfma_f32_16x16x32_bf16 v[118:121], v[176:179], v[200:203], v[118:121]
	v_mfma_f32_16x16x32_bf16 v[114:117], v[184:187], v[200:203], v[114:117]
	s_waitcnt lgkmcnt(3)
	v_mfma_f32_16x16x32_bf16 v[110:113], v[176:179], v[210:213], v[110:113]
	v_mfma_f32_16x16x32_bf16 v[106:109], v[184:187], v[210:213], v[106:109]
	s_waitcnt lgkmcnt(1)
	v_mfma_f32_16x16x32_bf16 v[102:105], v[176:179], v[218:221], v[102:105]
	v_mfma_f32_16x16x32_bf16 v[98:101], v[184:187], v[218:221], v[98:101]
	v_mfma_f32_16x16x32_bf16 v[126:129], v[180:183], v[196:199], v[126:129]
	v_mfma_f32_16x16x32_bf16 v[122:125], v[188:191], v[196:199], v[122:125]
	v_mfma_f32_16x16x32_bf16 v[118:121], v[180:183], v[204:207], v[118:121]
	v_mfma_f32_16x16x32_bf16 v[114:117], v[188:191], v[204:207], v[114:117]
	v_mfma_f32_16x16x32_bf16 v[110:113], v[180:183], v[214:217], v[110:113]
	v_mfma_f32_16x16x32_bf16 v[106:109], v[188:191], v[214:217], v[106:109]
	s_waitcnt lgkmcnt(0)
	v_mfma_f32_16x16x32_bf16 v[102:105], v[180:183], v[222:225], v[102:105]
	v_mfma_f32_16x16x32_bf16 v[98:101], v[188:191], v[222:225], v[98:101]
	s_setprio 0
	s_barrier
	s_add_i32 s57, 0, 0x1c000
	s_add_i32 s9, s9, s39
	v_add_u32_e32 v175, s57, v173
	v_lshl_add_u64 v[244:245], v[246:247], 0, s[16:17]
	s_mov_b32 m0, s9
	ds_read_b128 v[228:231], v175
	ds_read_b128 v[232:235], v175 offset:1024
	ds_read_b128 v[236:239], v175 offset:2048
	ds_read_b128 v[240:243], v175 offset:3072
	global_load_lds_dwordx4 v[244:245], off
	v_lshl_add_u64 v[244:245], v[248:249], 0, s[16:17]
	s_add_i32 m0, s9, 0x2000
	s_nop 0
	global_load_lds_dwordx4 v[244:245], off
	s_barrier
	s_setprio 1
	s_waitcnt lgkmcnt(3)
	v_mfma_f32_16x16x32_bf16 v[94:97], v[228:231], v[192:195], v[94:97]
	s_waitcnt lgkmcnt(1)
	v_mfma_f32_16x16x32_bf16 v[90:93], v[236:239], v[192:195], v[90:93]
	v_mfma_f32_16x16x32_bf16 v[86:89], v[228:231], v[200:203], v[86:89]
	v_mfma_f32_16x16x32_bf16 v[82:85], v[236:239], v[200:203], v[82:85]
	v_mfma_f32_16x16x32_bf16 v[78:81], v[228:231], v[210:213], v[78:81]
	v_mfma_f32_16x16x32_bf16 v[74:77], v[236:239], v[210:213], v[74:77]
	v_mfma_f32_16x16x32_bf16 v[70:73], v[228:231], v[218:221], v[70:73]
	v_mfma_f32_16x16x32_bf16 v[66:69], v[236:239], v[218:221], v[66:69]
	v_mfma_f32_16x16x32_bf16 v[94:97], v[232:235], v[196:199], v[94:97]
	s_waitcnt lgkmcnt(0)
	v_mfma_f32_16x16x32_bf16 v[90:93], v[240:243], v[196:199], v[90:93]
	v_mfma_f32_16x16x32_bf16 v[86:89], v[232:235], v[204:207], v[86:89]
	v_mfma_f32_16x16x32_bf16 v[82:85], v[240:243], v[204:207], v[82:85]
	v_mfma_f32_16x16x32_bf16 v[78:81], v[232:235], v[214:217], v[78:81]
	v_mfma_f32_16x16x32_bf16 v[74:77], v[240:243], v[214:217], v[74:77]
	v_mfma_f32_16x16x32_bf16 v[70:73], v[232:235], v[222:225], v[70:73]
	v_mfma_f32_16x16x32_bf16 v[66:69], v[240:243], v[222:225], v[66:69]
	s_setprio 0
	s_mov_b32 m0, s55
	v_lshl_add_u64 v[244:245], v[250:251], 0, s[16:17]
	s_barrier
	ds_read_b128 v[192:195], v174 offset:49152
	ds_read_b128 v[196:199], v174 offset:50176
	ds_read_b128 v[200:203], v174 offset:51200
	ds_read_b128 v[204:207], v174 offset:52224
	ds_read_b128 v[210:213], v174 offset:53248
	ds_read_b128 v[214:217], v174 offset:54272
	ds_read_b128 v[218:221], v174 offset:55296
	ds_read_b128 v[222:225], v174 offset:56320
	global_load_lds_dwordx4 v[244:245], off
	v_lshl_add_u64 v[244:245], v[252:253], 0, s[16:17]
	s_mov_b32 m0, s56
	s_nop 0
	global_load_lds_dwordx4 v[244:245], off
	s_barrier
	s_setprio 1
	s_waitcnt lgkmcnt(7)
	v_mfma_f32_16x16x32_bf16 v[62:65], v[176:179], v[192:195], v[62:65]
	v_mfma_f32_16x16x32_bf16 v[58:61], v[184:187], v[192:195], v[58:61]
	s_waitcnt lgkmcnt(5)
	v_mfma_f32_16x16x32_bf16 v[54:57], v[176:179], v[200:203], v[54:57]
	v_mfma_f32_16x16x32_bf16 v[50:53], v[184:187], v[200:203], v[50:53]
	s_waitcnt lgkmcnt(3)
	v_mfma_f32_16x16x32_bf16 v[46:49], v[176:179], v[210:213], v[46:49]
	v_mfma_f32_16x16x32_bf16 v[42:45], v[184:187], v[210:213], v[42:45]
	s_waitcnt lgkmcnt(1)
	v_mfma_f32_16x16x32_bf16 v[38:41], v[176:179], v[218:221], v[38:41]
	v_mfma_f32_16x16x32_bf16 v[34:37], v[184:187], v[218:221], v[34:37]
	v_mfma_f32_16x16x32_bf16 v[62:65], v[180:183], v[196:199], v[62:65]
	v_mfma_f32_16x16x32_bf16 v[58:61], v[188:191], v[196:199], v[58:61]
	v_mfma_f32_16x16x32_bf16 v[54:57], v[180:183], v[204:207], v[54:57]
	v_mfma_f32_16x16x32_bf16 v[50:53], v[188:191], v[204:207], v[50:53]
	v_mfma_f32_16x16x32_bf16 v[46:49], v[180:183], v[214:217], v[46:49]
	v_mfma_f32_16x16x32_bf16 v[42:45], v[188:191], v[214:217], v[42:45]
	s_waitcnt lgkmcnt(0)
	v_mfma_f32_16x16x32_bf16 v[38:41], v[180:183], v[222:225], v[38:41]
	v_mfma_f32_16x16x32_bf16 v[34:37], v[188:191], v[222:225], v[34:37]
	s_setprio 0
	s_barrier
	v_lshl_add_u64 v[170:171], v[170:171], 0, s[18:19]
	s_add_i32 s9, s57, s39
	v_lshl_add_u64 v[176:177], v[170:171], 0, v[134:135]
	s_mov_b32 m0, s9
	v_lshl_add_u64 v[170:171], v[170:171], 0, v[144:145]
	global_load_lds_dwordx4 v[176:177], off
	s_add_i32 m0, s9, 0x2000
	s_nop 0
	global_load_lds_dwordx4 v[170:171], off
	s_waitcnt vmcnt(6)
	s_barrier
	s_setprio 1
	v_mfma_f32_16x16x32_bf16 v[30:33], v[228:231], v[192:195], v[30:33]
	v_mfma_f32_16x16x32_bf16 v[26:29], v[236:239], v[192:195], v[26:29]
	v_mfma_f32_16x16x32_bf16 v[22:25], v[228:231], v[200:203], v[22:25]
	v_mfma_f32_16x16x32_bf16 v[18:21], v[236:239], v[200:203], v[18:21]
	v_mfma_f32_16x16x32_bf16 v[14:17], v[228:231], v[210:213], v[14:17]
	v_mfma_f32_16x16x32_bf16 v[10:13], v[236:239], v[210:213], v[10:13]
	v_mfma_f32_16x16x32_bf16 v[6:9], v[228:231], v[218:221], v[6:9]
	v_mfma_f32_16x16x32_bf16 v[2:5], v[236:239], v[218:221], v[2:5]
	v_mfma_f32_16x16x32_bf16 v[30:33], v[232:235], v[196:199], v[30:33]
	v_mfma_f32_16x16x32_bf16 v[26:29], v[240:243], v[196:199], v[26:29]
	v_mfma_f32_16x16x32_bf16 v[22:25], v[232:235], v[204:207], v[22:25]
	v_mfma_f32_16x16x32_bf16 v[18:21], v[240:243], v[204:207], v[18:21]
	v_mfma_f32_16x16x32_bf16 v[14:17], v[232:235], v[214:217], v[14:17]
	v_mfma_f32_16x16x32_bf16 v[10:13], v[240:243], v[214:217], v[10:13]
	v_mfma_f32_16x16x32_bf16 v[6:9], v[232:235], v[222:225], v[6:9]
	v_mfma_f32_16x16x32_bf16 v[2:5], v[240:243], v[222:225], v[2:5]
	s_setprio 0
	s_add_i32 s8, s8, 2
	s_add_u32 s6, s6, 0x100
	s_addc_u32 s7, s7, 0
	s_cmp_lt_u32 s8, 14
	s_barrier
	s_cbranch_scc1 .LBB0_914
	s_waitcnt vmcnt(0)
	s_cmpk_gt_u32 s38, 0xff
	s_cbranch_scc1 .LBB0_917
	s_barrier

.LBB0_1128:
	s_add_u32 s38, s6, 0xf8cd0080
	s_addc_u32 s39, s7, -1
	s_cmp_lg_u32 s37, 40
	s_cselect_b32 s39, s39, 0
	s_cselect_b32 s38, s38, 0
	s_add_i32 s40, 0, 0x10000
	v_add_u32_e32 v164, s40, v169
	ds_read_b128 v[172:175], v164
	ds_read_b128 v[176:179], v164 offset:1024
	ds_read_b128 v[180:183], v164 offset:2048
	ds_read_b128 v[184:187], v164 offset:3072
	v_lshl_add_u64 v[240:241], v[150:151], 0, s[38:39]
	v_lshl_add_u64 v[164:165], v[148:149], 0, s[38:39]
	v_lshl_add_u64 v[222:223], v[152:153], 0, s[6:7]
	s_add_i32 m0, s28, 0xc000
	ds_read_b128 v[188:191], v170
	ds_read_b128 v[192:195], v170 offset:1024
	ds_read_b128 v[196:199], v170 offset:2048
	ds_read_b128 v[200:203], v170 offset:3072
	ds_read_b128 v[204:207], v170 offset:4096
	ds_read_b128 v[210:213], v170 offset:5120
	ds_read_b128 v[214:217], v170 offset:6144
	ds_read_b128 v[218:221], v170 offset:7168
	global_load_lds_dwordx4 v[222:223], off
	v_lshl_add_u64 v[222:223], v[162:163], 0, s[6:7]
	s_add_i32 m0, s28, 0xe000
	s_nop 0
	global_load_lds_dwordx4 v[222:223], off
	s_waitcnt lgkmcnt(8)
	s_barrier
	s_setprio 1
	s_waitcnt lgkmcnt(7)
	v_mfma_f32_16x16x32_bf16 v[126:129], v[172:175], v[188:191], v[126:129]
	v_mfma_f32_16x16x32_bf16 v[122:125], v[180:183], v[188:191], v[122:125]
	s_waitcnt lgkmcnt(5)
	v_mfma_f32_16x16x32_bf16 v[118:121], v[172:175], v[196:199], v[118:121]
	v_mfma_f32_16x16x32_bf16 v[114:117], v[180:183], v[196:199], v[114:117]
	s_waitcnt lgkmcnt(3)
	v_mfma_f32_16x16x32_bf16 v[110:113], v[172:175], v[204:207], v[110:113]
	v_mfma_f32_16x16x32_bf16 v[106:109], v[180:183], v[204:207], v[106:109]
	s_waitcnt lgkmcnt(1)
	v_mfma_f32_16x16x32_bf16 v[102:105], v[172:175], v[214:217], v[102:105]
	v_mfma_f32_16x16x32_bf16 v[98:101], v[180:183], v[214:217], v[98:101]
	v_mfma_f32_16x16x32_bf16 v[126:129], v[176:179], v[192:195], v[126:129]
	v_mfma_f32_16x16x32_bf16 v[122:125], v[184:187], v[192:195], v[122:125]
	v_mfma_f32_16x16x32_bf16 v[118:121], v[176:179], v[200:203], v[118:121]
	v_mfma_f32_16x16x32_bf16 v[114:117], v[184:187], v[200:203], v[114:117]
	v_mfma_f32_16x16x32_bf16 v[110:113], v[176:179], v[210:213], v[110:113]
	v_mfma_f32_16x16x32_bf16 v[106:109], v[184:187], v[210:213], v[106:109]
	s_waitcnt lgkmcnt(0)
	v_mfma_f32_16x16x32_bf16 v[102:105], v[176:179], v[218:221], v[102:105]
	v_mfma_f32_16x16x32_bf16 v[98:101], v[184:187], v[218:221], v[98:101]
	s_setprio 0
	s_barrier
	s_add_i32 s38, 0, 0x14000
	s_add_i32 s39, s40, s27
	v_add_u32_e32 v171, s38, v169
	v_lshl_add_u64 v[242:243], v[164:165], 0, v[138:139]
	s_mov_b32 m0, s39
	ds_read_b128 v[222:225], v171
	ds_read_b128 v[228:231], v171 offset:1024
	ds_read_b128 v[232:235], v171 offset:2048
	ds_read_b128 v[236:239], v171 offset:3072
	global_load_lds_dwordx4 v[242:243], off
	v_lshl_add_u64 v[244:245], v[164:165], 0, v[146:147]
	s_add_i32 m0, s39, 0x2000
	s_nop 0
	global_load_lds_dwordx4 v[244:245], off
	s_barrier
	s_setprio 1
	s_waitcnt lgkmcnt(3)
	v_mfma_f32_16x16x32_bf16 v[94:97], v[222:225], v[188:191], v[94:97]
	s_waitcnt lgkmcnt(1)
	v_mfma_f32_16x16x32_bf16 v[90:93], v[232:235], v[188:191], v[90:93]
	v_mfma_f32_16x16x32_bf16 v[86:89], v[222:225], v[196:199], v[86:89]
	v_mfma_f32_16x16x32_bf16 v[82:85], v[232:235], v[196:199], v[82:85]
	v_mfma_f32_16x16x32_bf16 v[78:81], v[222:225], v[204:207], v[78:81]
	v_mfma_f32_16x16x32_bf16 v[74:77], v[232:235], v[204:207], v[74:77]
	v_mfma_f32_16x16x32_bf16 v[70:73], v[222:225], v[214:217], v[70:73]
	v_mfma_f32_16x16x32_bf16 v[66:69], v[232:235], v[214:217], v[66:69]
	v_mfma_f32_16x16x32_bf16 v[94:97], v[228:231], v[192:195], v[94:97]
	s_waitcnt lgkmcnt(0)
	v_mfma_f32_16x16x32_bf16 v[90:93], v[236:239], v[192:195], v[90:93]
	v_mfma_f32_16x16x32_bf16 v[86:89], v[228:231], v[200:203], v[86:89]
	v_mfma_f32_16x16x32_bf16 v[82:85], v[236:239], v[200:203], v[82:85]
	v_mfma_f32_16x16x32_bf16 v[78:81], v[228:231], v[210:213], v[78:81]
	v_mfma_f32_16x16x32_bf16 v[74:77], v[236:239], v[210:213], v[74:77]
	v_mfma_f32_16x16x32_bf16 v[70:73], v[228:231], v[218:221], v[70:73]
	v_mfma_f32_16x16x32_bf16 v[66:69], v[236:239], v[218:221], v[66:69]
	s_setprio 0
	s_mov_b32 m0, s28
	v_lshl_add_u64 v[246:247], v[240:241], 0, v[138:139]
	s_barrier
	ds_read_b128 v[188:191], v170 offset:16384
	ds_read_b128 v[192:195], v170 offset:17408
	ds_read_b128 v[196:199], v170 offset:18432
	ds_read_b128 v[200:203], v170 offset:19456
	ds_read_b128 v[204:207], v170 offset:20480
	ds_read_b128 v[210:213], v170 offset:21504
	ds_read_b128 v[214:217], v170 offset:22528
	ds_read_b128 v[218:221], v170 offset:23552
	global_load_lds_dwordx4 v[246:247], off
	v_lshl_add_u64 v[248:249], v[240:241], 0, v[146:147]
	s_mov_b32 m0, s29
	s_nop 0
	global_load_lds_dwordx4 v[248:249], off
	s_barrier
	s_setprio 1
	s_waitcnt lgkmcnt(7)
	v_mfma_f32_16x16x32_bf16 v[62:65], v[172:175], v[188:191], v[62:65]
	v_mfma_f32_16x16x32_bf16 v[58:61], v[180:183], v[188:191], v[58:61]
	s_waitcnt lgkmcnt(5)
	v_mfma_f32_16x16x32_bf16 v[54:57], v[172:175], v[196:199], v[54:57]
	v_mfma_f32_16x16x32_bf16 v[50:53], v[180:183], v[196:199], v[50:53]
	s_waitcnt lgkmcnt(3)
	v_mfma_f32_16x16x32_bf16 v[46:49], v[172:175], v[204:207], v[46:49]
	v_mfma_f32_16x16x32_bf16 v[42:45], v[180:183], v[204:207], v[42:45]
	s_waitcnt lgkmcnt(1)
	v_mfma_f32_16x16x32_bf16 v[38:41], v[172:175], v[214:217], v[38:41]
	v_mfma_f32_16x16x32_bf16 v[34:37], v[180:183], v[214:217], v[34:37]
	v_mfma_f32_16x16x32_bf16 v[62:65], v[176:179], v[192:195], v[62:65]
	v_mfma_f32_16x16x32_bf16 v[58:61], v[184:187], v[192:195], v[58:61]
	v_mfma_f32_16x16x32_bf16 v[54:57], v[176:179], v[200:203], v[54:57]
	v_mfma_f32_16x16x32_bf16 v[50:53], v[184:187], v[200:203], v[50:53]
	v_mfma_f32_16x16x32_bf16 v[46:49], v[176:179], v[210:213], v[46:49]
	v_mfma_f32_16x16x32_bf16 v[42:45], v[184:187], v[210:213], v[42:45]
	s_waitcnt lgkmcnt(0)
	v_mfma_f32_16x16x32_bf16 v[38:41], v[176:179], v[218:221], v[38:41]
	v_mfma_f32_16x16x32_bf16 v[34:37], v[184:187], v[218:221], v[34:37]
	s_setprio 0
	s_barrier
	v_lshl_add_u64 v[172:173], v[164:165], 0, s[16:17]
	s_add_i32 s38, s38, s27
	v_lshl_add_u64 v[174:175], v[172:173], 0, v[138:139]
	s_mov_b32 m0, s38
	v_lshl_add_u64 v[172:173], v[172:173], 0, v[146:147]
	global_load_lds_dwordx4 v[174:175], off
	s_add_i32 m0, s38, 0x2000
	s_nop 0
	global_load_lds_dwordx4 v[172:173], off
	s_waitcnt vmcnt(6)
	s_barrier
	s_setprio 1
	v_mfma_f32_16x16x32_bf16 v[30:33], v[222:225], v[188:191], v[30:33]
	v_mfma_f32_16x16x32_bf16 v[26:29], v[232:235], v[188:191], v[26:29]
	v_mfma_f32_16x16x32_bf16 v[22:25], v[222:225], v[196:199], v[22:25]
	v_mfma_f32_16x16x32_bf16 v[18:21], v[232:235], v[196:199], v[18:21]
	v_mfma_f32_16x16x32_bf16 v[14:17], v[222:225], v[204:207], v[14:17]
	v_mfma_f32_16x16x32_bf16 v[10:13], v[232:235], v[204:207], v[10:13]
	v_mfma_f32_16x16x32_bf16 v[6:9], v[222:225], v[214:217], v[6:9]
	v_mfma_f32_16x16x32_bf16 v[2:5], v[232:235], v[214:217], v[2:5]
	v_mfma_f32_16x16x32_bf16 v[30:33], v[228:231], v[192:195], v[30:33]
	v_mfma_f32_16x16x32_bf16 v[26:29], v[236:239], v[192:195], v[26:29]
	v_mfma_f32_16x16x32_bf16 v[22:25], v[228:231], v[200:203], v[22:25]
	v_mfma_f32_16x16x32_bf16 v[18:21], v[236:239], v[200:203], v[18:21]
	v_mfma_f32_16x16x32_bf16 v[14:17], v[228:231], v[210:213], v[14:17]
	v_mfma_f32_16x16x32_bf16 v[10:13], v[236:239], v[210:213], v[10:13]
	v_mfma_f32_16x16x32_bf16 v[6:9], v[228:231], v[218:221], v[6:9]
	v_mfma_f32_16x16x32_bf16 v[2:5], v[236:239], v[218:221], v[2:5]
	s_setprio 0
	s_add_i32 s38, 0, 0x18000
	v_add_u32_e32 v171, s38, v169
	s_barrier
	ds_read_b128 v[172:175], v171
	ds_read_b128 v[176:179], v171 offset:1024
	ds_read_b128 v[180:183], v171 offset:2048
	ds_read_b128 v[184:187], v171 offset:3072
	v_lshl_add_u64 v[222:223], v[240:241], 0, s[16:17]
	s_mov_b32 m0, s31
	v_lshl_add_u64 v[224:225], v[222:223], 0, v[138:139]
	ds_read_b128 v[188:191], v170 offset:32768
	ds_read_b128 v[192:195], v170 offset:33792
	ds_read_b128 v[196:199], v170 offset:34816
	ds_read_b128 v[200:203], v170 offset:35840
	ds_read_b128 v[204:207], v170 offset:36864
	ds_read_b128 v[210:213], v170 offset:37888
	ds_read_b128 v[214:217], v170 offset:38912
	ds_read_b128 v[218:221], v170 offset:39936
	global_load_lds_dwordx4 v[224:225], off
	v_lshl_add_u64 v[222:223], v[222:223], 0, v[146:147]
	s_mov_b32 m0, s34
	s_nop 0
	global_load_lds_dwordx4 v[222:223], off
	s_waitcnt lgkmcnt(8)
	s_barrier
	s_setprio 1
	s_waitcnt lgkmcnt(7)
	v_mfma_f32_16x16x32_bf16 v[126:129], v[172:175], v[188:191], v[126:129]
	v_mfma_f32_16x16x32_bf16 v[122:125], v[180:183], v[188:191], v[122:125]
	s_waitcnt lgkmcnt(5)
	v_mfma_f32_16x16x32_bf16 v[118:121], v[172:175], v[196:199], v[118:121]
	v_mfma_f32_16x16x32_bf16 v[114:117], v[180:183], v[196:199], v[114:117]
	s_waitcnt lgkmcnt(3)
	v_mfma_f32_16x16x32_bf16 v[110:113], v[172:175], v[204:207], v[110:113]
	v_mfma_f32_16x16x32_bf16 v[106:109], v[180:183], v[204:207], v[106:109]
	s_waitcnt lgkmcnt(1)
	v_mfma_f32_16x16x32_bf16 v[102:105], v[172:175], v[214:217], v[102:105]
	v_mfma_f32_16x16x32_bf16 v[98:101], v[180:183], v[214:217], v[98:101]
	v_mfma_f32_16x16x32_bf16 v[126:129], v[176:179], v[192:195], v[126:129]
	v_mfma_f32_16x16x32_bf16 v[122:125], v[184:187], v[192:195], v[122:125]
	v_mfma_f32_16x16x32_bf16 v[118:121], v[176:179], v[200:203], v[118:121]
	v_mfma_f32_16x16x32_bf16 v[114:117], v[184:187], v[200:203], v[114:117]
	v_mfma_f32_16x16x32_bf16 v[110:113], v[176:179], v[210:213], v[110:113]
	v_mfma_f32_16x16x32_bf16 v[106:109], v[184:187], v[210:213], v[106:109]
	s_waitcnt lgkmcnt(0)
	v_mfma_f32_16x16x32_bf16 v[102:105], v[176:179], v[218:221], v[102:105]
	v_mfma_f32_16x16x32_bf16 v[98:101], v[184:187], v[218:221], v[98:101]
	s_setprio 0
	s_barrier
	s_add_i32 s39, 0, 0x1c000
	s_add_i32 s38, s38, s27
	v_add_u32_e32 v171, s39, v169
	v_lshl_add_u64 v[240:241], v[242:243], 0, s[18:19]
	s_mov_b32 m0, s38
	ds_read_b128 v[222:225], v171
	ds_read_b128 v[228:231], v171 offset:1024
	ds_read_b128 v[232:235], v171 offset:2048
	ds_read_b128 v[236:239], v171 offset:3072
	global_load_lds_dwordx4 v[240:241], off
	v_lshl_add_u64 v[240:241], v[244:245], 0, s[18:19]
	s_add_i32 m0, s38, 0x2000
	s_nop 0
	global_load_lds_dwordx4 v[240:241], off
	s_barrier
	s_setprio 1
	s_waitcnt lgkmcnt(3)
	v_mfma_f32_16x16x32_bf16 v[94:97], v[222:225], v[188:191], v[94:97]
	s_waitcnt lgkmcnt(1)
	v_mfma_f32_16x16x32_bf16 v[90:93], v[232:235], v[188:191], v[90:93]
	v_mfma_f32_16x16x32_bf16 v[86:89], v[222:225], v[196:199], v[86:89]
	v_mfma_f32_16x16x32_bf16 v[82:85], v[232:235], v[196:199], v[82:85]
	v_mfma_f32_16x16x32_bf16 v[78:81], v[222:225], v[204:207], v[78:81]
	v_mfma_f32_16x16x32_bf16 v[74:77], v[232:235], v[204:207], v[74:77]
	v_mfma_f32_16x16x32_bf16 v[70:73], v[222:225], v[214:217], v[70:73]
	v_mfma_f32_16x16x32_bf16 v[66:69], v[232:235], v[214:217], v[66:69]
	v_mfma_f32_16x16x32_bf16 v[94:97], v[228:231], v[192:195], v[94:97]
	s_waitcnt lgkmcnt(0)
	v_mfma_f32_16x16x32_bf16 v[90:93], v[236:239], v[192:195], v[90:93]
	v_mfma_f32_16x16x32_bf16 v[86:89], v[228:231], v[200:203], v[86:89]
	v_mfma_f32_16x16x32_bf16 v[82:85], v[236:239], v[200:203], v[82:85]
	v_mfma_f32_16x16x32_bf16 v[78:81], v[228:231], v[210:213], v[78:81]
	v_mfma_f32_16x16x32_bf16 v[74:77], v[236:239], v[210:213], v[74:77]
	v_mfma_f32_16x16x32_bf16 v[70:73], v[228:231], v[218:221], v[70:73]
	v_mfma_f32_16x16x32_bf16 v[66:69], v[236:239], v[218:221], v[66:69]
	s_setprio 0
	s_mov_b32 m0, s35
	v_lshl_add_u64 v[240:241], v[246:247], 0, s[18:19]
	s_barrier
	ds_read_b128 v[188:191], v170 offset:49152
	ds_read_b128 v[192:195], v170 offset:50176
	ds_read_b128 v[196:199], v170 offset:51200
	ds_read_b128 v[200:203], v170 offset:52224
	ds_read_b128 v[204:207], v170 offset:53248
	ds_read_b128 v[210:213], v170 offset:54272
	ds_read_b128 v[214:217], v170 offset:55296
	ds_read_b128 v[218:221], v170 offset:56320
	global_load_lds_dwordx4 v[240:241], off
	v_lshl_add_u64 v[240:241], v[248:249], 0, s[18:19]
	s_mov_b32 m0, s36
	s_nop 0
	global_load_lds_dwordx4 v[240:241], off
	s_barrier
	s_setprio 1
	s_waitcnt lgkmcnt(7)
	v_mfma_f32_16x16x32_bf16 v[62:65], v[172:175], v[188:191], v[62:65]
	v_mfma_f32_16x16x32_bf16 v[58:61], v[180:183], v[188:191], v[58:61]
	s_waitcnt lgkmcnt(5)
	v_mfma_f32_16x16x32_bf16 v[54:57], v[172:175], v[196:199], v[54:57]
	v_mfma_f32_16x16x32_bf16 v[50:53], v[180:183], v[196:199], v[50:53]
	s_waitcnt lgkmcnt(3)
	v_mfma_f32_16x16x32_bf16 v[46:49], v[172:175], v[204:207], v[46:49]
	v_mfma_f32_16x16x32_bf16 v[42:45], v[180:183], v[204:207], v[42:45]
	s_waitcnt lgkmcnt(1)
	v_mfma_f32_16x16x32_bf16 v[38:41], v[172:175], v[214:217], v[38:41]
	v_mfma_f32_16x16x32_bf16 v[34:37], v[180:183], v[214:217], v[34:37]
	v_mfma_f32_16x16x32_bf16 v[62:65], v[176:179], v[192:195], v[62:65]
	v_mfma_f32_16x16x32_bf16 v[58:61], v[184:187], v[192:195], v[58:61]
	v_mfma_f32_16x16x32_bf16 v[54:57], v[176:179], v[200:203], v[54:57]
	v_mfma_f32_16x16x32_bf16 v[50:53], v[184:187], v[200:203], v[50:53]
	v_mfma_f32_16x16x32_bf16 v[46:49], v[176:179], v[210:213], v[46:49]
	v_mfma_f32_16x16x32_bf16 v[42:45], v[184:187], v[210:213], v[42:45]
	s_waitcnt lgkmcnt(0)
	v_mfma_f32_16x16x32_bf16 v[38:41], v[176:179], v[218:221], v[38:41]
	v_mfma_f32_16x16x32_bf16 v[34:37], v[184:187], v[218:221], v[34:37]
	s_setprio 0
	s_barrier
	v_lshl_add_u64 v[164:165], v[164:165], 0, s[20:21]
	s_add_i32 s38, s39, s27
	v_lshl_add_u64 v[172:173], v[164:165], 0, v[138:139]
	s_mov_b32 m0, s38
	v_lshl_add_u64 v[164:165], v[164:165], 0, v[146:147]
	global_load_lds_dwordx4 v[172:173], off
	s_add_i32 m0, s38, 0x2000
	s_nop 0
	global_load_lds_dwordx4 v[164:165], off
	s_waitcnt vmcnt(6)
	s_barrier
	s_setprio 1
	v_mfma_f32_16x16x32_bf16 v[30:33], v[222:225], v[188:191], v[30:33]
	v_mfma_f32_16x16x32_bf16 v[26:29], v[232:235], v[188:191], v[26:29]
	v_mfma_f32_16x16x32_bf16 v[22:25], v[222:225], v[196:199], v[22:25]
	v_mfma_f32_16x16x32_bf16 v[18:21], v[232:235], v[196:199], v[18:21]
	v_mfma_f32_16x16x32_bf16 v[14:17], v[222:225], v[204:207], v[14:17]
	v_mfma_f32_16x16x32_bf16 v[10:13], v[232:235], v[204:207], v[10:13]
	v_mfma_f32_16x16x32_bf16 v[6:9], v[222:225], v[214:217], v[6:9]
	v_mfma_f32_16x16x32_bf16 v[2:5], v[232:235], v[214:217], v[2:5]
	v_mfma_f32_16x16x32_bf16 v[30:33], v[228:231], v[192:195], v[30:33]
	v_mfma_f32_16x16x32_bf16 v[26:29], v[236:239], v[192:195], v[26:29]
	v_mfma_f32_16x16x32_bf16 v[22:25], v[228:231], v[200:203], v[22:25]
	v_mfma_f32_16x16x32_bf16 v[18:21], v[236:239], v[200:203], v[18:21]
	v_mfma_f32_16x16x32_bf16 v[14:17], v[228:231], v[210:213], v[14:17]
	v_mfma_f32_16x16x32_bf16 v[10:13], v[236:239], v[210:213], v[10:13]
	v_mfma_f32_16x16x32_bf16 v[6:9], v[228:231], v[218:221], v[6:9]
	v_mfma_f32_16x16x32_bf16 v[2:5], v[236:239], v[218:221], v[2:5]
	s_setprio 0
	s_add_i32 s37, s37, 2
	s_add_u32 s6, s6, 0x100
	s_addc_u32 s7, s7, 0
	s_cmp_lt_u32 s37, 42
	s_barrier
	s_cbranch_scc1 .LBB0_1128
	s_waitcnt vmcnt(0)
	s_cmpk_gt_u32 s26, 0xff
	s_cbranch_scc1 .LBB0_1131
	s_barrier

.LBB0_1271:
	s_cmpk_eq_i32 s6, 0x700
	v_lshl_add_u64 v[170:171], v[162:163], 0, s[6:7]
	v_lshl_add_u64 v[170:171], v[170:171], 0, s[18:19]
	s_cselect_b64 vcc, -1, 0
	s_add_i32 s25, 0, 0x10000
	v_cndmask_b32_e32 v245, v171, v153, vcc
	v_add_u32_e32 v171, s25, v173
	ds_read_b128 v[176:179], v171
	ds_read_b128 v[180:183], v171 offset:1024
	ds_read_b128 v[184:187], v171 offset:2048
	ds_read_b128 v[188:191], v171 offset:3072
	v_cndmask_b32_e32 v244, v170, v152, vcc
	v_lshl_add_u64 v[170:171], v[168:169], 0, s[6:7]
	v_cndmask_b32_e32 v171, v171, v151, vcc
	v_cndmask_b32_e32 v170, v170, v150, vcc
	v_lshl_add_u64 v[228:229], v[164:165], 0, s[6:7]
	s_add_i32 m0, s20, 0xc000
	ds_read_b128 v[192:195], v174
	ds_read_b128 v[196:199], v174 offset:1024
	ds_read_b128 v[200:203], v174 offset:2048
	ds_read_b128 v[204:207], v174 offset:3072
	ds_read_b128 v[210:213], v174 offset:4096
	ds_read_b128 v[214:217], v174 offset:5120
	ds_read_b128 v[218:221], v174 offset:6144
	ds_read_b128 v[222:225], v174 offset:7168
	global_load_lds_dwordx4 v[228:229], off
	v_lshl_add_u64 v[228:229], v[166:167], 0, s[6:7]
	s_add_i32 m0, s20, 0xe000
	s_nop 0
	global_load_lds_dwordx4 v[228:229], off
	s_waitcnt lgkmcnt(8)
	s_barrier
	s_setprio 1
	s_waitcnt lgkmcnt(7)
	v_mfma_f32_16x16x32_bf16 v[126:129], v[176:179], v[192:195], v[126:129]
	v_mfma_f32_16x16x32_bf16 v[122:125], v[184:187], v[192:195], v[122:125]
	s_waitcnt lgkmcnt(5)
	v_mfma_f32_16x16x32_bf16 v[118:121], v[176:179], v[200:203], v[118:121]
	v_mfma_f32_16x16x32_bf16 v[114:117], v[184:187], v[200:203], v[114:117]
	s_waitcnt lgkmcnt(3)
	v_mfma_f32_16x16x32_bf16 v[110:113], v[176:179], v[210:213], v[110:113]
	v_mfma_f32_16x16x32_bf16 v[106:109], v[184:187], v[210:213], v[106:109]
	s_waitcnt lgkmcnt(1)
	v_mfma_f32_16x16x32_bf16 v[102:105], v[176:179], v[218:221], v[102:105]
	v_mfma_f32_16x16x32_bf16 v[98:101], v[184:187], v[218:221], v[98:101]
	v_mfma_f32_16x16x32_bf16 v[126:129], v[180:183], v[196:199], v[126:129]
	v_mfma_f32_16x16x32_bf16 v[122:125], v[188:191], v[196:199], v[122:125]
	v_mfma_f32_16x16x32_bf16 v[118:121], v[180:183], v[204:207], v[118:121]
	v_mfma_f32_16x16x32_bf16 v[114:117], v[188:191], v[204:207], v[114:117]
	v_mfma_f32_16x16x32_bf16 v[110:113], v[180:183], v[214:217], v[110:113]
	v_mfma_f32_16x16x32_bf16 v[106:109], v[188:191], v[214:217], v[106:109]
	s_waitcnt lgkmcnt(0)
	v_mfma_f32_16x16x32_bf16 v[102:105], v[180:183], v[222:225], v[102:105]
	v_mfma_f32_16x16x32_bf16 v[98:101], v[188:191], v[222:225], v[98:101]
	s_setprio 0
	s_barrier
	s_add_i32 s41, 0, 0x14000
	s_add_i32 s25, s25, s35
	v_add_u32_e32 v175, s41, v173
	v_lshl_add_u64 v[246:247], v[170:171], 0, v[138:139]
	s_mov_b32 m0, s25
	ds_read_b128 v[228:231], v175
	ds_read_b128 v[232:235], v175 offset:1024
	ds_read_b128 v[236:239], v175 offset:2048
	ds_read_b128 v[240:243], v175 offset:3072
	global_load_lds_dwordx4 v[246:247], off
	v_lshl_add_u64 v[248:249], v[170:171], 0, v[148:149]
	s_add_i32 m0, s25, 0x2000
	s_nop 0
	global_load_lds_dwordx4 v[248:249], off
	s_barrier
	s_setprio 1
	s_waitcnt lgkmcnt(3)
	v_mfma_f32_16x16x32_bf16 v[94:97], v[228:231], v[192:195], v[94:97]
	s_waitcnt lgkmcnt(1)
	v_mfma_f32_16x16x32_bf16 v[90:93], v[236:239], v[192:195], v[90:93]
	v_mfma_f32_16x16x32_bf16 v[86:89], v[228:231], v[200:203], v[86:89]
	v_mfma_f32_16x16x32_bf16 v[82:85], v[236:239], v[200:203], v[82:85]
	v_mfma_f32_16x16x32_bf16 v[78:81], v[228:231], v[210:213], v[78:81]
	v_mfma_f32_16x16x32_bf16 v[74:77], v[236:239], v[210:213], v[74:77]
	v_mfma_f32_16x16x32_bf16 v[70:73], v[228:231], v[218:221], v[70:73]
	v_mfma_f32_16x16x32_bf16 v[66:69], v[236:239], v[218:221], v[66:69]
	v_mfma_f32_16x16x32_bf16 v[94:97], v[232:235], v[196:199], v[94:97]
	s_waitcnt lgkmcnt(0)
	v_mfma_f32_16x16x32_bf16 v[90:93], v[240:243], v[196:199], v[90:93]
	v_mfma_f32_16x16x32_bf16 v[86:89], v[232:235], v[204:207], v[86:89]
	v_mfma_f32_16x16x32_bf16 v[82:85], v[240:243], v[204:207], v[82:85]
	v_mfma_f32_16x16x32_bf16 v[78:81], v[232:235], v[214:217], v[78:81]
	v_mfma_f32_16x16x32_bf16 v[74:77], v[240:243], v[214:217], v[74:77]
	v_mfma_f32_16x16x32_bf16 v[70:73], v[232:235], v[222:225], v[70:73]
	v_mfma_f32_16x16x32_bf16 v[66:69], v[240:243], v[222:225], v[66:69]
	s_setprio 0
	s_mov_b32 m0, s20
	v_lshl_add_u64 v[250:251], v[244:245], 0, v[138:139]
	s_barrier
	ds_read_b128 v[192:195], v174 offset:16384
	ds_read_b128 v[196:199], v174 offset:17408
	ds_read_b128 v[200:203], v174 offset:18432
	ds_read_b128 v[204:207], v174 offset:19456
	ds_read_b128 v[210:213], v174 offset:20480
	ds_read_b128 v[214:217], v174 offset:21504
	ds_read_b128 v[218:221], v174 offset:22528
	ds_read_b128 v[222:225], v174 offset:23552
	global_load_lds_dwordx4 v[250:251], off
	v_lshl_add_u64 v[252:253], v[244:245], 0, v[148:149]
	s_mov_b32 m0, s36
	s_nop 0
	global_load_lds_dwordx4 v[252:253], off
	s_barrier
	s_setprio 1
	s_waitcnt lgkmcnt(7)
	v_mfma_f32_16x16x32_bf16 v[62:65], v[176:179], v[192:195], v[62:65]
	v_mfma_f32_16x16x32_bf16 v[58:61], v[184:187], v[192:195], v[58:61]
	s_waitcnt lgkmcnt(5)
	v_mfma_f32_16x16x32_bf16 v[54:57], v[176:179], v[200:203], v[54:57]
	v_mfma_f32_16x16x32_bf16 v[50:53], v[184:187], v[200:203], v[50:53]
	s_waitcnt lgkmcnt(3)
	v_mfma_f32_16x16x32_bf16 v[46:49], v[176:179], v[210:213], v[46:49]
	v_mfma_f32_16x16x32_bf16 v[42:45], v[184:187], v[210:213], v[42:45]
	s_waitcnt lgkmcnt(1)
	v_mfma_f32_16x16x32_bf16 v[38:41], v[176:179], v[218:221], v[38:41]
	v_mfma_f32_16x16x32_bf16 v[34:37], v[184:187], v[218:221], v[34:37]
	v_mfma_f32_16x16x32_bf16 v[62:65], v[180:183], v[196:199], v[62:65]
	v_mfma_f32_16x16x32_bf16 v[58:61], v[188:191], v[196:199], v[58:61]
	v_mfma_f32_16x16x32_bf16 v[54:57], v[180:183], v[204:207], v[54:57]
	v_mfma_f32_16x16x32_bf16 v[50:53], v[188:191], v[204:207], v[50:53]
	v_mfma_f32_16x16x32_bf16 v[46:49], v[180:183], v[214:217], v[46:49]
	v_mfma_f32_16x16x32_bf16 v[42:45], v[188:191], v[214:217], v[42:45]
	s_waitcnt lgkmcnt(0)
	v_mfma_f32_16x16x32_bf16 v[38:41], v[180:183], v[222:225], v[38:41]
	v_mfma_f32_16x16x32_bf16 v[34:37], v[188:191], v[222:225], v[34:37]
	s_setprio 0
	s_barrier
	v_lshl_add_u64 v[176:177], v[170:171], 0, s[12:13]
	s_add_i32 s25, s41, s35
	v_lshl_add_u64 v[178:179], v[176:177], 0, v[138:139]
	s_mov_b32 m0, s25
	v_lshl_add_u64 v[176:177], v[176:177], 0, v[148:149]
	global_load_lds_dwordx4 v[178:179], off
	s_add_i32 m0, s25, 0x2000
	s_nop 0
	global_load_lds_dwordx4 v[176:177], off
	s_waitcnt vmcnt(6)
	s_barrier
	s_setprio 1
	v_mfma_f32_16x16x32_bf16 v[30:33], v[228:231], v[192:195], v[30:33]
	v_mfma_f32_16x16x32_bf16 v[26:29], v[236:239], v[192:195], v[26:29]
	v_mfma_f32_16x16x32_bf16 v[22:25], v[228:231], v[200:203], v[22:25]
	v_mfma_f32_16x16x32_bf16 v[18:21], v[236:239], v[200:203], v[18:21]
	v_mfma_f32_16x16x32_bf16 v[14:17], v[228:231], v[210:213], v[14:17]
	v_mfma_f32_16x16x32_bf16 v[10:13], v[236:239], v[210:213], v[10:13]
	v_mfma_f32_16x16x32_bf16 v[6:9], v[228:231], v[218:221], v[6:9]
	v_mfma_f32_16x16x32_bf16 v[2:5], v[236:239], v[218:221], v[2:5]
	v_mfma_f32_16x16x32_bf16 v[30:33], v[232:235], v[196:199], v[30:33]
	v_mfma_f32_16x16x32_bf16 v[26:29], v[240:243], v[196:199], v[26:29]
	v_mfma_f32_16x16x32_bf16 v[22:25], v[232:235], v[204:207], v[22:25]
	v_mfma_f32_16x16x32_bf16 v[18:21], v[240:243], v[204:207], v[18:21]
	v_mfma_f32_16x16x32_bf16 v[14:17], v[232:235], v[214:217], v[14:17]
	v_mfma_f32_16x16x32_bf16 v[10:13], v[240:243], v[214:217], v[10:13]
	v_mfma_f32_16x16x32_bf16 v[6:9], v[232:235], v[222:225], v[6:9]
	v_mfma_f32_16x16x32_bf16 v[2:5], v[240:243], v[222:225], v[2:5]
	s_setprio 0
	s_add_i32 s25, 0, 0x18000
	v_add_u32_e32 v175, s25, v173
	s_barrier
	ds_read_b128 v[176:179], v175
	ds_read_b128 v[180:183], v175 offset:1024
	ds_read_b128 v[184:187], v175 offset:2048
	ds_read_b128 v[188:191], v175 offset:3072
	v_lshl_add_u64 v[228:229], v[244:245], 0, s[12:13]
	s_mov_b32 m0, s37
	v_lshl_add_u64 v[230:231], v[228:229], 0, v[138:139]
	ds_read_b128 v[192:195], v174 offset:32768
	ds_read_b128 v[196:199], v174 offset:33792
	ds_read_b128 v[200:203], v174 offset:34816
	ds_read_b128 v[204:207], v174 offset:35840
	ds_read_b128 v[210:213], v174 offset:36864
	ds_read_b128 v[214:217], v174 offset:37888
	ds_read_b128 v[218:221], v174 offset:38912
	ds_read_b128 v[222:225], v174 offset:39936
	global_load_lds_dwordx4 v[230:231], off
	v_lshl_add_u64 v[228:229], v[228:229], 0, v[148:149]
	s_mov_b32 m0, s38
	s_nop 0
	global_load_lds_dwordx4 v[228:229], off
	s_waitcnt lgkmcnt(8)
	s_barrier
	s_setprio 1
	s_waitcnt lgkmcnt(7)
	v_mfma_f32_16x16x32_bf16 v[126:129], v[176:179], v[192:195], v[126:129]
	v_mfma_f32_16x16x32_bf16 v[122:125], v[184:187], v[192:195], v[122:125]
	s_waitcnt lgkmcnt(5)
	v_mfma_f32_16x16x32_bf16 v[118:121], v[176:179], v[200:203], v[118:121]
	v_mfma_f32_16x16x32_bf16 v[114:117], v[184:187], v[200:203], v[114:117]
	s_waitcnt lgkmcnt(3)
	v_mfma_f32_16x16x32_bf16 v[110:113], v[176:179], v[210:213], v[110:113]
	v_mfma_f32_16x16x32_bf16 v[106:109], v[184:187], v[210:213], v[106:109]
	s_waitcnt lgkmcnt(1)
	v_mfma_f32_16x16x32_bf16 v[102:105], v[176:179], v[218:221], v[102:105]
	v_mfma_f32_16x16x32_bf16 v[98:101], v[184:187], v[218:221], v[98:101]
	v_mfma_f32_16x16x32_bf16 v[126:129], v[180:183], v[196:199], v[126:129]
	v_mfma_f32_16x16x32_bf16 v[122:125], v[188:191], v[196:199], v[122:125]
	v_mfma_f32_16x16x32_bf16 v[118:121], v[180:183], v[204:207], v[118:121]
	v_mfma_f32_16x16x32_bf16 v[114:117], v[188:191], v[204:207], v[114:117]
	v_mfma_f32_16x16x32_bf16 v[110:113], v[180:183], v[214:217], v[110:113]
	v_mfma_f32_16x16x32_bf16 v[106:109], v[188:191], v[214:217], v[106:109]
	s_waitcnt lgkmcnt(0)
	v_mfma_f32_16x16x32_bf16 v[102:105], v[180:183], v[222:225], v[102:105]
	v_mfma_f32_16x16x32_bf16 v[98:101], v[188:191], v[222:225], v[98:101]
	s_setprio 0
	s_barrier
	s_add_i32 s41, 0, 0x1c000
	s_add_i32 s25, s25, s35
	v_add_u32_e32 v175, s41, v173
	v_lshl_add_u64 v[244:245], v[246:247], 0, s[14:15]
	s_mov_b32 m0, s25
	ds_read_b128 v[228:231], v175
	ds_read_b128 v[232:235], v175 offset:1024
	ds_read_b128 v[236:239], v175 offset:2048
	ds_read_b128 v[240:243], v175 offset:3072
	global_load_lds_dwordx4 v[244:245], off
	v_lshl_add_u64 v[244:245], v[248:249], 0, s[14:15]
	s_add_i32 m0, s25, 0x2000
	s_nop 0
	global_load_lds_dwordx4 v[244:245], off
	s_barrier
	s_setprio 1
	s_waitcnt lgkmcnt(3)
	v_mfma_f32_16x16x32_bf16 v[94:97], v[228:231], v[192:195], v[94:97]
	s_waitcnt lgkmcnt(1)
	v_mfma_f32_16x16x32_bf16 v[90:93], v[236:239], v[192:195], v[90:93]
	v_mfma_f32_16x16x32_bf16 v[86:89], v[228:231], v[200:203], v[86:89]
	v_mfma_f32_16x16x32_bf16 v[82:85], v[236:239], v[200:203], v[82:85]
	v_mfma_f32_16x16x32_bf16 v[78:81], v[228:231], v[210:213], v[78:81]
	v_mfma_f32_16x16x32_bf16 v[74:77], v[236:239], v[210:213], v[74:77]
	v_mfma_f32_16x16x32_bf16 v[70:73], v[228:231], v[218:221], v[70:73]
	v_mfma_f32_16x16x32_bf16 v[66:69], v[236:239], v[218:221], v[66:69]
	v_mfma_f32_16x16x32_bf16 v[94:97], v[232:235], v[196:199], v[94:97]
	s_waitcnt lgkmcnt(0)
	v_mfma_f32_16x16x32_bf16 v[90:93], v[240:243], v[196:199], v[90:93]
	v_mfma_f32_16x16x32_bf16 v[86:89], v[232:235], v[204:207], v[86:89]
	v_mfma_f32_16x16x32_bf16 v[82:85], v[240:243], v[204:207], v[82:85]
	v_mfma_f32_16x16x32_bf16 v[78:81], v[232:235], v[214:217], v[78:81]
	v_mfma_f32_16x16x32_bf16 v[74:77], v[240:243], v[214:217], v[74:77]
	v_mfma_f32_16x16x32_bf16 v[70:73], v[232:235], v[222:225], v[70:73]
	v_mfma_f32_16x16x32_bf16 v[66:69], v[240:243], v[222:225], v[66:69]
	s_setprio 0
	s_mov_b32 m0, s39
	v_lshl_add_u64 v[244:245], v[250:251], 0, s[14:15]
	s_barrier
	ds_read_b128 v[192:195], v174 offset:49152
	ds_read_b128 v[196:199], v174 offset:50176
	ds_read_b128 v[200:203], v174 offset:51200
	ds_read_b128 v[204:207], v174 offset:52224
	ds_read_b128 v[210:213], v174 offset:53248
	ds_read_b128 v[214:217], v174 offset:54272
	ds_read_b128 v[218:221], v174 offset:55296
	ds_read_b128 v[222:225], v174 offset:56320
	global_load_lds_dwordx4 v[244:245], off
	v_lshl_add_u64 v[244:245], v[252:253], 0, s[14:15]
	s_mov_b32 m0, s40
	s_nop 0
	global_load_lds_dwordx4 v[244:245], off
	s_barrier
	s_setprio 1
	s_waitcnt lgkmcnt(7)
	v_mfma_f32_16x16x32_bf16 v[62:65], v[176:179], v[192:195], v[62:65]
	v_mfma_f32_16x16x32_bf16 v[58:61], v[184:187], v[192:195], v[58:61]
	s_waitcnt lgkmcnt(5)
	v_mfma_f32_16x16x32_bf16 v[54:57], v[176:179], v[200:203], v[54:57]
	v_mfma_f32_16x16x32_bf16 v[50:53], v[184:187], v[200:203], v[50:53]
	s_waitcnt lgkmcnt(3)
	v_mfma_f32_16x16x32_bf16 v[46:49], v[176:179], v[210:213], v[46:49]
	v_mfma_f32_16x16x32_bf16 v[42:45], v[184:187], v[210:213], v[42:45]
	s_waitcnt lgkmcnt(1)
	v_mfma_f32_16x16x32_bf16 v[38:41], v[176:179], v[218:221], v[38:41]
	v_mfma_f32_16x16x32_bf16 v[34:37], v[184:187], v[218:221], v[34:37]
	v_mfma_f32_16x16x32_bf16 v[62:65], v[180:183], v[196:199], v[62:65]
	v_mfma_f32_16x16x32_bf16 v[58:61], v[188:191], v[196:199], v[58:61]
	v_mfma_f32_16x16x32_bf16 v[54:57], v[180:183], v[204:207], v[54:57]
	v_mfma_f32_16x16x32_bf16 v[50:53], v[188:191], v[204:207], v[50:53]
	v_mfma_f32_16x16x32_bf16 v[46:49], v[180:183], v[214:217], v[46:49]
	v_mfma_f32_16x16x32_bf16 v[42:45], v[188:191], v[214:217], v[42:45]
	s_waitcnt lgkmcnt(0)
	v_mfma_f32_16x16x32_bf16 v[38:41], v[180:183], v[222:225], v[38:41]
	v_mfma_f32_16x16x32_bf16 v[34:37], v[188:191], v[222:225], v[34:37]
	s_setprio 0
	s_barrier
	v_lshl_add_u64 v[170:171], v[170:171], 0, s[16:17]
	s_add_i32 s25, s41, s35
	v_lshl_add_u64 v[176:177], v[170:171], 0, v[138:139]
	s_mov_b32 m0, s25
	v_lshl_add_u64 v[170:171], v[170:171], 0, v[148:149]
	global_load_lds_dwordx4 v[176:177], off
	s_add_i32 m0, s25, 0x2000
	s_nop 0
	global_load_lds_dwordx4 v[170:171], off
	s_waitcnt vmcnt(6)
	s_barrier
	s_setprio 1
	v_mfma_f32_16x16x32_bf16 v[30:33], v[228:231], v[192:195], v[30:33]
	v_mfma_f32_16x16x32_bf16 v[26:29], v[236:239], v[192:195], v[26:29]
	v_mfma_f32_16x16x32_bf16 v[22:25], v[228:231], v[200:203], v[22:25]
	v_mfma_f32_16x16x32_bf16 v[18:21], v[236:239], v[200:203], v[18:21]
	v_mfma_f32_16x16x32_bf16 v[14:17], v[228:231], v[210:213], v[14:17]
	v_mfma_f32_16x16x32_bf16 v[10:13], v[236:239], v[210:213], v[10:13]
	v_mfma_f32_16x16x32_bf16 v[6:9], v[228:231], v[218:221], v[6:9]
	v_mfma_f32_16x16x32_bf16 v[2:5], v[236:239], v[218:221], v[2:5]
	v_mfma_f32_16x16x32_bf16 v[30:33], v[232:235], v[196:199], v[30:33]
	v_mfma_f32_16x16x32_bf16 v[26:29], v[240:243], v[196:199], v[26:29]
	v_mfma_f32_16x16x32_bf16 v[22:25], v[232:235], v[204:207], v[22:25]
	v_mfma_f32_16x16x32_bf16 v[18:21], v[240:243], v[204:207], v[18:21]
	v_mfma_f32_16x16x32_bf16 v[14:17], v[232:235], v[214:217], v[14:17]
	v_mfma_f32_16x16x32_bf16 v[10:13], v[240:243], v[214:217], v[10:13]
	v_mfma_f32_16x16x32_bf16 v[6:9], v[232:235], v[222:225], v[6:9]
	v_mfma_f32_16x16x32_bf16 v[2:5], v[240:243], v[222:225], v[2:5]
	s_setprio 0
	s_add_i32 s24, s24, 2
	s_add_u32 s6, s6, 0x100
	s_addc_u32 s7, s7, 0
	s_cmp_lt_u32 s24, 14
	s_barrier
	s_cbranch_scc1 .LBB0_1271
	s_waitcnt vmcnt(0)
	s_cmpk_gt_u32 s27, 0xff
	s_cbranch_scc1 .LBB0_1274
	s_barrier

.LBB0_1645:
	s_add_u32 s33, s6, 0xfbd40080
	s_addc_u32 s34, s7, -1
	s_cmp_lg_u32 s31, 12
	s_cselect_b32 s35, s34, 0
	s_cselect_b32 s34, s33, 0
	s_add_i32 s33, 0, 0x10000
	v_add_u32_e32 v164, s33, v167
	ds_read_b128 v[170:173], v164
	ds_read_b128 v[174:177], v164 offset:1024
	ds_read_b128 v[178:181], v164 offset:2048
	ds_read_b128 v[182:185], v164 offset:3072
	v_lshl_add_u64 v[206:207], v[150:151], 0, s[34:35]
	v_lshl_add_u64 v[164:165], v[148:149], 0, s[34:35]
	v_lshl_add_u64 v[222:223], v[152:153], 0, s[6:7]
	s_add_i32 m0, s17, 0xc000
	ds_read_b128 v[186:189], v168
	ds_read_b128 v[190:193], v168 offset:1024
	ds_read_b128 v[194:197], v168 offset:2048
	ds_read_b128 v[198:201], v168 offset:3072
	ds_read_b128 v[202:205], v168 offset:4096
	ds_read_b128 v[210:213], v168 offset:5120
	ds_read_b128 v[214:217], v168 offset:6144
	ds_read_b128 v[218:221], v168 offset:7168
	global_load_lds_dwordx4 v[222:223], off
	v_lshl_add_u64 v[222:223], v[162:163], 0, s[6:7]
	s_add_i32 m0, s17, 0xe000
	s_nop 0
	global_load_lds_dwordx4 v[222:223], off
	s_waitcnt lgkmcnt(8)
	s_barrier
	s_setprio 1
	s_waitcnt lgkmcnt(7)
	v_mfma_f32_16x16x32_bf16 v[126:129], v[170:173], v[186:189], v[126:129]
	v_mfma_f32_16x16x32_bf16 v[122:125], v[178:181], v[186:189], v[122:125]
	s_waitcnt lgkmcnt(5)
	v_mfma_f32_16x16x32_bf16 v[118:121], v[170:173], v[194:197], v[118:121]
	v_mfma_f32_16x16x32_bf16 v[114:117], v[178:181], v[194:197], v[114:117]
	s_waitcnt lgkmcnt(3)
	v_mfma_f32_16x16x32_bf16 v[110:113], v[170:173], v[202:205], v[110:113]
	v_mfma_f32_16x16x32_bf16 v[106:109], v[178:181], v[202:205], v[106:109]
	s_waitcnt lgkmcnt(1)
	v_mfma_f32_16x16x32_bf16 v[102:105], v[170:173], v[214:217], v[102:105]
	v_mfma_f32_16x16x32_bf16 v[98:101], v[178:181], v[214:217], v[98:101]
	v_mfma_f32_16x16x32_bf16 v[126:129], v[174:177], v[190:193], v[126:129]
	v_mfma_f32_16x16x32_bf16 v[122:125], v[182:185], v[190:193], v[122:125]
	v_mfma_f32_16x16x32_bf16 v[118:121], v[174:177], v[198:201], v[118:121]
	v_mfma_f32_16x16x32_bf16 v[114:117], v[182:185], v[198:201], v[114:117]
	v_mfma_f32_16x16x32_bf16 v[110:113], v[174:177], v[210:213], v[110:113]
	v_mfma_f32_16x16x32_bf16 v[106:109], v[182:185], v[210:213], v[106:109]
	s_waitcnt lgkmcnt(0)
	v_mfma_f32_16x16x32_bf16 v[102:105], v[174:177], v[218:221], v[102:105]
	v_mfma_f32_16x16x32_bf16 v[98:101], v[182:185], v[218:221], v[98:101]
	s_setprio 0
	s_barrier
	s_add_i32 s34, 0, 0x14000
	s_add_i32 s33, s33, s25
	v_add_u32_e32 v169, s34, v167
	v_lshl_add_u64 v[240:241], v[164:165], 0, v[138:139]
	s_mov_b32 m0, s33
	ds_read_b128 v[222:225], v169
	ds_read_b128 v[228:231], v169 offset:1024
	ds_read_b128 v[232:235], v169 offset:2048
	ds_read_b128 v[236:239], v169 offset:3072
	global_load_lds_dwordx4 v[240:241], off
	v_lshl_add_u64 v[242:243], v[164:165], 0, v[146:147]
	s_add_i32 m0, s33, 0x2000
	s_nop 0
	global_load_lds_dwordx4 v[242:243], off
	s_barrier
	s_setprio 1
	s_waitcnt lgkmcnt(3)
	v_mfma_f32_16x16x32_bf16 v[94:97], v[222:225], v[186:189], v[94:97]
	s_waitcnt lgkmcnt(1)
	v_mfma_f32_16x16x32_bf16 v[90:93], v[232:235], v[186:189], v[90:93]
	v_mfma_f32_16x16x32_bf16 v[86:89], v[222:225], v[194:197], v[86:89]
	v_mfma_f32_16x16x32_bf16 v[82:85], v[232:235], v[194:197], v[82:85]
	v_mfma_f32_16x16x32_bf16 v[78:81], v[222:225], v[202:205], v[78:81]
	v_mfma_f32_16x16x32_bf16 v[74:77], v[232:235], v[202:205], v[74:77]
	v_mfma_f32_16x16x32_bf16 v[70:73], v[222:225], v[214:217], v[70:73]
	v_mfma_f32_16x16x32_bf16 v[66:69], v[232:235], v[214:217], v[66:69]
	v_mfma_f32_16x16x32_bf16 v[94:97], v[228:231], v[190:193], v[94:97]
	s_waitcnt lgkmcnt(0)
	v_mfma_f32_16x16x32_bf16 v[90:93], v[236:239], v[190:193], v[90:93]
	v_mfma_f32_16x16x32_bf16 v[86:89], v[228:231], v[198:201], v[86:89]
	v_mfma_f32_16x16x32_bf16 v[82:85], v[236:239], v[198:201], v[82:85]
	v_mfma_f32_16x16x32_bf16 v[78:81], v[228:231], v[210:213], v[78:81]
	v_mfma_f32_16x16x32_bf16 v[74:77], v[236:239], v[210:213], v[74:77]
	v_mfma_f32_16x16x32_bf16 v[70:73], v[228:231], v[218:221], v[70:73]
	v_mfma_f32_16x16x32_bf16 v[66:69], v[236:239], v[218:221], v[66:69]
	s_setprio 0
	s_mov_b32 m0, s17
	v_lshl_add_u64 v[244:245], v[206:207], 0, v[138:139]
	s_barrier
	ds_read_b128 v[186:189], v168 offset:16384
	ds_read_b128 v[190:193], v168 offset:17408
	ds_read_b128 v[194:197], v168 offset:18432
	ds_read_b128 v[198:201], v168 offset:19456
	ds_read_b128 v[202:205], v168 offset:20480
	ds_read_b128 v[210:213], v168 offset:21504
	ds_read_b128 v[214:217], v168 offset:22528
	ds_read_b128 v[218:221], v168 offset:23552
	global_load_lds_dwordx4 v[244:245], off
	v_lshl_add_u64 v[246:247], v[206:207], 0, v[146:147]
	s_mov_b32 m0, s26
	s_nop 0
	global_load_lds_dwordx4 v[246:247], off
	s_barrier
	s_setprio 1
	s_waitcnt lgkmcnt(7)
	v_mfma_f32_16x16x32_bf16 v[62:65], v[170:173], v[186:189], v[62:65]
	v_mfma_f32_16x16x32_bf16 v[58:61], v[178:181], v[186:189], v[58:61]
	s_waitcnt lgkmcnt(5)
	v_mfma_f32_16x16x32_bf16 v[54:57], v[170:173], v[194:197], v[54:57]
	v_mfma_f32_16x16x32_bf16 v[50:53], v[178:181], v[194:197], v[50:53]
	s_waitcnt lgkmcnt(3)
	v_mfma_f32_16x16x32_bf16 v[46:49], v[170:173], v[202:205], v[46:49]
	v_mfma_f32_16x16x32_bf16 v[42:45], v[178:181], v[202:205], v[42:45]
	s_waitcnt lgkmcnt(1)
	v_mfma_f32_16x16x32_bf16 v[38:41], v[170:173], v[214:217], v[38:41]
	v_mfma_f32_16x16x32_bf16 v[34:37], v[178:181], v[214:217], v[34:37]
	v_mfma_f32_16x16x32_bf16 v[62:65], v[174:177], v[190:193], v[62:65]
	v_mfma_f32_16x16x32_bf16 v[58:61], v[182:185], v[190:193], v[58:61]
	v_mfma_f32_16x16x32_bf16 v[54:57], v[174:177], v[198:201], v[54:57]
	v_mfma_f32_16x16x32_bf16 v[50:53], v[182:185], v[198:201], v[50:53]
	v_mfma_f32_16x16x32_bf16 v[46:49], v[174:177], v[210:213], v[46:49]
	v_mfma_f32_16x16x32_bf16 v[42:45], v[182:185], v[210:213], v[42:45]
	s_waitcnt lgkmcnt(0)
	v_mfma_f32_16x16x32_bf16 v[38:41], v[174:177], v[218:221], v[38:41]
	v_mfma_f32_16x16x32_bf16 v[34:37], v[182:185], v[218:221], v[34:37]
	s_setprio 0
	s_barrier
	v_lshl_add_u64 v[170:171], v[164:165], 0, s[8:9]
	s_add_i32 s33, s34, s25
	v_lshl_add_u64 v[172:173], v[170:171], 0, v[138:139]
	s_mov_b32 m0, s33
	v_lshl_add_u64 v[170:171], v[170:171], 0, v[146:147]
	global_load_lds_dwordx4 v[172:173], off
	s_add_i32 m0, s33, 0x2000
	s_nop 0
	global_load_lds_dwordx4 v[170:171], off
	s_waitcnt vmcnt(6)
	s_barrier
	s_setprio 1
	v_mfma_f32_16x16x32_bf16 v[30:33], v[222:225], v[186:189], v[30:33]
	v_mfma_f32_16x16x32_bf16 v[26:29], v[232:235], v[186:189], v[26:29]
	v_mfma_f32_16x16x32_bf16 v[22:25], v[222:225], v[194:197], v[22:25]
	v_mfma_f32_16x16x32_bf16 v[18:21], v[232:235], v[194:197], v[18:21]
	v_mfma_f32_16x16x32_bf16 v[14:17], v[222:225], v[202:205], v[14:17]
	v_mfma_f32_16x16x32_bf16 v[10:13], v[232:235], v[202:205], v[10:13]
	v_mfma_f32_16x16x32_bf16 v[6:9], v[222:225], v[214:217], v[6:9]
	v_mfma_f32_16x16x32_bf16 v[2:5], v[232:235], v[214:217], v[2:5]
	v_mfma_f32_16x16x32_bf16 v[30:33], v[228:231], v[190:193], v[30:33]
	v_mfma_f32_16x16x32_bf16 v[26:29], v[236:239], v[190:193], v[26:29]
	v_mfma_f32_16x16x32_bf16 v[22:25], v[228:231], v[198:201], v[22:25]
	v_mfma_f32_16x16x32_bf16 v[18:21], v[236:239], v[198:201], v[18:21]
	v_mfma_f32_16x16x32_bf16 v[14:17], v[228:231], v[210:213], v[14:17]
	v_mfma_f32_16x16x32_bf16 v[10:13], v[236:239], v[210:213], v[10:13]
	v_mfma_f32_16x16x32_bf16 v[6:9], v[228:231], v[218:221], v[6:9]
	v_mfma_f32_16x16x32_bf16 v[2:5], v[236:239], v[218:221], v[2:5]
	s_setprio 0
	s_add_i32 s33, 0, 0x18000
	v_add_u32_e32 v169, s33, v167
	s_barrier
	ds_read_b128 v[170:173], v169
	ds_read_b128 v[174:177], v169 offset:1024
	ds_read_b128 v[178:181], v169 offset:2048
	ds_read_b128 v[182:185], v169 offset:3072
	v_lshl_add_u64 v[206:207], v[206:207], 0, s[8:9]
	s_mov_b32 m0, s27
	v_lshl_add_u64 v[222:223], v[206:207], 0, v[138:139]
	ds_read_b128 v[186:189], v168 offset:32768
	ds_read_b128 v[190:193], v168 offset:33792
	ds_read_b128 v[194:197], v168 offset:34816
	ds_read_b128 v[198:201], v168 offset:35840
	ds_read_b128 v[202:205], v168 offset:36864
	ds_read_b128 v[210:213], v168 offset:37888
	ds_read_b128 v[214:217], v168 offset:38912
	ds_read_b128 v[218:221], v168 offset:39936
	global_load_lds_dwordx4 v[222:223], off
	v_lshl_add_u64 v[206:207], v[206:207], 0, v[146:147]
	s_mov_b32 m0, s28
	s_nop 0
	global_load_lds_dwordx4 v[206:207], off
	s_waitcnt lgkmcnt(8)
	s_barrier
	s_setprio 1
	s_waitcnt lgkmcnt(7)
	v_mfma_f32_16x16x32_bf16 v[126:129], v[170:173], v[186:189], v[126:129]
	v_mfma_f32_16x16x32_bf16 v[122:125], v[178:181], v[186:189], v[122:125]
	s_waitcnt lgkmcnt(5)
	v_mfma_f32_16x16x32_bf16 v[118:121], v[170:173], v[194:197], v[118:121]
	v_mfma_f32_16x16x32_bf16 v[114:117], v[178:181], v[194:197], v[114:117]
	s_waitcnt lgkmcnt(3)
	v_mfma_f32_16x16x32_bf16 v[110:113], v[170:173], v[202:205], v[110:113]
	v_mfma_f32_16x16x32_bf16 v[106:109], v[178:181], v[202:205], v[106:109]
	s_waitcnt lgkmcnt(1)
	v_mfma_f32_16x16x32_bf16 v[102:105], v[170:173], v[214:217], v[102:105]
	v_mfma_f32_16x16x32_bf16 v[98:101], v[178:181], v[214:217], v[98:101]
	v_mfma_f32_16x16x32_bf16 v[126:129], v[174:177], v[190:193], v[126:129]
	v_mfma_f32_16x16x32_bf16 v[122:125], v[182:185], v[190:193], v[122:125]
	v_mfma_f32_16x16x32_bf16 v[118:121], v[174:177], v[198:201], v[118:121]
	v_mfma_f32_16x16x32_bf16 v[114:117], v[182:185], v[198:201], v[114:117]
	v_mfma_f32_16x16x32_bf16 v[110:113], v[174:177], v[210:213], v[110:113]
	v_mfma_f32_16x16x32_bf16 v[106:109], v[182:185], v[210:213], v[106:109]
	s_waitcnt lgkmcnt(0)
	v_mfma_f32_16x16x32_bf16 v[102:105], v[174:177], v[218:221], v[102:105]
	v_mfma_f32_16x16x32_bf16 v[98:101], v[182:185], v[218:221], v[98:101]
	s_setprio 0
	s_barrier
	s_add_i32 s34, 0, 0x1c000
	s_add_i32 s33, s33, s25
	v_add_u32_e32 v169, s34, v167
	v_lshl_add_u64 v[206:207], v[240:241], 0, s[10:11]
	s_mov_b32 m0, s33
	ds_read_b128 v[222:225], v169
	ds_read_b128 v[228:231], v169 offset:1024
	ds_read_b128 v[232:235], v169 offset:2048
	ds_read_b128 v[236:239], v169 offset:3072
	global_load_lds_dwordx4 v[206:207], off
	v_lshl_add_u64 v[206:207], v[242:243], 0, s[10:11]
	s_add_i32 m0, s33, 0x2000
	s_nop 0
	global_load_lds_dwordx4 v[206:207], off
	s_barrier
	s_setprio 1
	s_waitcnt lgkmcnt(3)
	v_mfma_f32_16x16x32_bf16 v[94:97], v[222:225], v[186:189], v[94:97]
	s_waitcnt lgkmcnt(1)
	v_mfma_f32_16x16x32_bf16 v[90:93], v[232:235], v[186:189], v[90:93]
	v_mfma_f32_16x16x32_bf16 v[86:89], v[222:225], v[194:197], v[86:89]
	v_mfma_f32_16x16x32_bf16 v[82:85], v[232:235], v[194:197], v[82:85]
	v_mfma_f32_16x16x32_bf16 v[78:81], v[222:225], v[202:205], v[78:81]
	v_mfma_f32_16x16x32_bf16 v[74:77], v[232:235], v[202:205], v[74:77]
	v_mfma_f32_16x16x32_bf16 v[70:73], v[222:225], v[214:217], v[70:73]
	v_mfma_f32_16x16x32_bf16 v[66:69], v[232:235], v[214:217], v[66:69]
	v_mfma_f32_16x16x32_bf16 v[94:97], v[228:231], v[190:193], v[94:97]
	s_waitcnt lgkmcnt(0)
	v_mfma_f32_16x16x32_bf16 v[90:93], v[236:239], v[190:193], v[90:93]
	v_mfma_f32_16x16x32_bf16 v[86:89], v[228:231], v[198:201], v[86:89]
	v_mfma_f32_16x16x32_bf16 v[82:85], v[236:239], v[198:201], v[82:85]
	v_mfma_f32_16x16x32_bf16 v[78:81], v[228:231], v[210:213], v[78:81]
	v_mfma_f32_16x16x32_bf16 v[74:77], v[236:239], v[210:213], v[74:77]
	v_mfma_f32_16x16x32_bf16 v[70:73], v[228:231], v[218:221], v[70:73]
	v_mfma_f32_16x16x32_bf16 v[66:69], v[236:239], v[218:221], v[66:69]
	s_setprio 0
	s_mov_b32 m0, s29
	v_lshl_add_u64 v[206:207], v[244:245], 0, s[10:11]
	s_barrier
	ds_read_b128 v[186:189], v168 offset:49152
	ds_read_b128 v[190:193], v168 offset:50176
	ds_read_b128 v[194:197], v168 offset:51200
	ds_read_b128 v[198:201], v168 offset:52224
	ds_read_b128 v[202:205], v168 offset:53248
	ds_read_b128 v[210:213], v168 offset:54272
	ds_read_b128 v[214:217], v168 offset:55296
	ds_read_b128 v[218:221], v168 offset:56320
	global_load_lds_dwordx4 v[206:207], off
	v_lshl_add_u64 v[206:207], v[246:247], 0, s[10:11]
	s_mov_b32 m0, s30
	s_nop 0
	global_load_lds_dwordx4 v[206:207], off
	s_barrier
	s_setprio 1
	s_waitcnt lgkmcnt(7)
	v_mfma_f32_16x16x32_bf16 v[62:65], v[170:173], v[186:189], v[62:65]
	v_mfma_f32_16x16x32_bf16 v[58:61], v[178:181], v[186:189], v[58:61]
	s_waitcnt lgkmcnt(5)
	v_mfma_f32_16x16x32_bf16 v[54:57], v[170:173], v[194:197], v[54:57]
	v_mfma_f32_16x16x32_bf16 v[50:53], v[178:181], v[194:197], v[50:53]
	s_waitcnt lgkmcnt(3)
	v_mfma_f32_16x16x32_bf16 v[46:49], v[170:173], v[202:205], v[46:49]
	v_mfma_f32_16x16x32_bf16 v[42:45], v[178:181], v[202:205], v[42:45]
	s_waitcnt lgkmcnt(1)
	v_mfma_f32_16x16x32_bf16 v[38:41], v[170:173], v[214:217], v[38:41]
	v_mfma_f32_16x16x32_bf16 v[34:37], v[178:181], v[214:217], v[34:37]
	v_mfma_f32_16x16x32_bf16 v[62:65], v[174:177], v[190:193], v[62:65]
	v_mfma_f32_16x16x32_bf16 v[58:61], v[182:185], v[190:193], v[58:61]
	v_mfma_f32_16x16x32_bf16 v[54:57], v[174:177], v[198:201], v[54:57]
	v_mfma_f32_16x16x32_bf16 v[50:53], v[182:185], v[198:201], v[50:53]
	v_mfma_f32_16x16x32_bf16 v[46:49], v[174:177], v[210:213], v[46:49]
	v_mfma_f32_16x16x32_bf16 v[42:45], v[182:185], v[210:213], v[42:45]
	s_waitcnt lgkmcnt(0)
	v_mfma_f32_16x16x32_bf16 v[38:41], v[174:177], v[218:221], v[38:41]
	v_mfma_f32_16x16x32_bf16 v[34:37], v[182:185], v[218:221], v[34:37]
	s_setprio 0
	s_barrier
	v_lshl_add_u64 v[164:165], v[164:165], 0, s[12:13]
	s_add_i32 s33, s34, s25
	v_lshl_add_u64 v[170:171], v[164:165], 0, v[138:139]
	s_mov_b32 m0, s33
	v_lshl_add_u64 v[164:165], v[164:165], 0, v[146:147]
	global_load_lds_dwordx4 v[170:171], off
	s_add_i32 m0, s33, 0x2000
	s_nop 0
	global_load_lds_dwordx4 v[164:165], off
	s_waitcnt vmcnt(6)
	s_barrier
	s_setprio 1
	v_mfma_f32_16x16x32_bf16 v[30:33], v[222:225], v[186:189], v[30:33]
	v_mfma_f32_16x16x32_bf16 v[26:29], v[232:235], v[186:189], v[26:29]
	v_mfma_f32_16x16x32_bf16 v[22:25], v[222:225], v[194:197], v[22:25]
	v_mfma_f32_16x16x32_bf16 v[18:21], v[232:235], v[194:197], v[18:21]
	v_mfma_f32_16x16x32_bf16 v[14:17], v[222:225], v[202:205], v[14:17]
	v_mfma_f32_16x16x32_bf16 v[10:13], v[232:235], v[202:205], v[10:13]
	v_mfma_f32_16x16x32_bf16 v[6:9], v[222:225], v[214:217], v[6:9]
	v_mfma_f32_16x16x32_bf16 v[2:5], v[232:235], v[214:217], v[2:5]
	v_mfma_f32_16x16x32_bf16 v[30:33], v[228:231], v[190:193], v[30:33]
	v_mfma_f32_16x16x32_bf16 v[26:29], v[236:239], v[190:193], v[26:29]
	v_mfma_f32_16x16x32_bf16 v[22:25], v[228:231], v[198:201], v[22:25]
	v_mfma_f32_16x16x32_bf16 v[18:21], v[236:239], v[198:201], v[18:21]
	v_mfma_f32_16x16x32_bf16 v[14:17], v[228:231], v[210:213], v[14:17]
	v_mfma_f32_16x16x32_bf16 v[10:13], v[236:239], v[210:213], v[10:13]
	v_mfma_f32_16x16x32_bf16 v[6:9], v[228:231], v[218:221], v[6:9]
	v_mfma_f32_16x16x32_bf16 v[2:5], v[236:239], v[218:221], v[2:5]
	s_setprio 0
	s_add_i32 s31, s31, 2
	s_add_u32 s6, s6, 0x100
	s_addc_u32 s7, s7, 0
	s_cmp_lt_u32 s31, 14
	s_barrier
	s_cbranch_scc1 .LBB0_1645
	s_waitcnt vmcnt(0)
	s_cmpk_gt_u32 s24, 0xff
	s_cbranch_scc1 .LBB0_1648
	s_barrier

.LBB0_1788:
	s_cmpk_eq_i32 s4, 0x700
	v_lshl_add_u64 v[170:171], v[162:163], 0, s[4:5]
	v_lshl_add_u64 v[170:171], v[170:171], 0, s[22:23]
	s_cselect_b64 vcc, -1, 0
	s_add_i32 s7, 0, 0x10000
	v_cndmask_b32_e32 v245, v171, v153, vcc
	v_add_u32_e32 v171, s7, v173
	ds_read_b128 v[176:179], v171
	ds_read_b128 v[180:183], v171 offset:1024
	ds_read_b128 v[184:187], v171 offset:2048
	ds_read_b128 v[188:191], v171 offset:3072
	v_cndmask_b32_e32 v244, v170, v152, vcc
	v_lshl_add_u64 v[170:171], v[168:169], 0, s[4:5]
	v_cndmask_b32_e32 v171, v171, v151, vcc
	v_cndmask_b32_e32 v170, v170, v150, vcc
	v_lshl_add_u64 v[228:229], v[164:165], 0, s[4:5]
	s_add_i32 m0, s34, 0xc000
	ds_read_b128 v[192:195], v174
	ds_read_b128 v[196:199], v174 offset:1024
	ds_read_b128 v[200:203], v174 offset:2048
	ds_read_b128 v[204:207], v174 offset:3072
	ds_read_b128 v[210:213], v174 offset:4096
	ds_read_b128 v[214:217], v174 offset:5120
	ds_read_b128 v[218:221], v174 offset:6144
	ds_read_b128 v[222:225], v174 offset:7168
	global_load_lds_dwordx4 v[228:229], off
	v_lshl_add_u64 v[228:229], v[166:167], 0, s[4:5]
	s_add_i32 m0, s34, 0xe000
	s_nop 0
	global_load_lds_dwordx4 v[228:229], off
	s_waitcnt lgkmcnt(8)
	s_barrier
	s_setprio 1
	s_waitcnt lgkmcnt(7)
	v_mfma_f32_16x16x32_bf16 v[126:129], v[176:179], v[192:195], v[126:129]
	v_mfma_f32_16x16x32_bf16 v[122:125], v[184:187], v[192:195], v[122:125]
	s_waitcnt lgkmcnt(5)
	v_mfma_f32_16x16x32_bf16 v[118:121], v[176:179], v[200:203], v[118:121]
	v_mfma_f32_16x16x32_bf16 v[114:117], v[184:187], v[200:203], v[114:117]
	s_waitcnt lgkmcnt(3)
	v_mfma_f32_16x16x32_bf16 v[110:113], v[176:179], v[210:213], v[110:113]
	v_mfma_f32_16x16x32_bf16 v[106:109], v[184:187], v[210:213], v[106:109]
	s_waitcnt lgkmcnt(1)
	v_mfma_f32_16x16x32_bf16 v[102:105], v[176:179], v[218:221], v[102:105]
	v_mfma_f32_16x16x32_bf16 v[98:101], v[184:187], v[218:221], v[98:101]
	v_mfma_f32_16x16x32_bf16 v[126:129], v[180:183], v[196:199], v[126:129]
	v_mfma_f32_16x16x32_bf16 v[122:125], v[188:191], v[196:199], v[122:125]
	v_mfma_f32_16x16x32_bf16 v[118:121], v[180:183], v[204:207], v[118:121]
	v_mfma_f32_16x16x32_bf16 v[114:117], v[188:191], v[204:207], v[114:117]
	v_mfma_f32_16x16x32_bf16 v[110:113], v[180:183], v[214:217], v[110:113]
	v_mfma_f32_16x16x32_bf16 v[106:109], v[188:191], v[214:217], v[106:109]
	s_waitcnt lgkmcnt(0)
	v_mfma_f32_16x16x32_bf16 v[102:105], v[180:183], v[222:225], v[102:105]
	v_mfma_f32_16x16x32_bf16 v[98:101], v[188:191], v[222:225], v[98:101]
	s_setprio 0
	s_barrier
	s_add_i32 s57, 0, 0x14000
	s_add_i32 s7, s7, s39
	v_add_u32_e32 v175, s57, v173
	v_lshl_add_u64 v[246:247], v[170:171], 0, v[138:139]
	s_mov_b32 m0, s7
	ds_read_b128 v[228:231], v175
	ds_read_b128 v[232:235], v175 offset:1024
	ds_read_b128 v[236:239], v175 offset:2048
	ds_read_b128 v[240:243], v175 offset:3072
	global_load_lds_dwordx4 v[246:247], off
	v_lshl_add_u64 v[248:249], v[170:171], 0, v[148:149]
	s_add_i32 m0, s7, 0x2000
	s_nop 0
	global_load_lds_dwordx4 v[248:249], off
	s_barrier
	s_setprio 1
	s_waitcnt lgkmcnt(3)
	v_mfma_f32_16x16x32_bf16 v[94:97], v[228:231], v[192:195], v[94:97]
	s_waitcnt lgkmcnt(1)
	v_mfma_f32_16x16x32_bf16 v[90:93], v[236:239], v[192:195], v[90:93]
	v_mfma_f32_16x16x32_bf16 v[86:89], v[228:231], v[200:203], v[86:89]
	v_mfma_f32_16x16x32_bf16 v[82:85], v[236:239], v[200:203], v[82:85]
	v_mfma_f32_16x16x32_bf16 v[78:81], v[228:231], v[210:213], v[78:81]
	v_mfma_f32_16x16x32_bf16 v[74:77], v[236:239], v[210:213], v[74:77]
	v_mfma_f32_16x16x32_bf16 v[70:73], v[228:231], v[218:221], v[70:73]
	v_mfma_f32_16x16x32_bf16 v[66:69], v[236:239], v[218:221], v[66:69]
	v_mfma_f32_16x16x32_bf16 v[94:97], v[232:235], v[196:199], v[94:97]
	s_waitcnt lgkmcnt(0)
	v_mfma_f32_16x16x32_bf16 v[90:93], v[240:243], v[196:199], v[90:93]
	v_mfma_f32_16x16x32_bf16 v[86:89], v[232:235], v[204:207], v[86:89]
	v_mfma_f32_16x16x32_bf16 v[82:85], v[240:243], v[204:207], v[82:85]
	v_mfma_f32_16x16x32_bf16 v[78:81], v[232:235], v[214:217], v[78:81]
	v_mfma_f32_16x16x32_bf16 v[74:77], v[240:243], v[214:217], v[74:77]
	v_mfma_f32_16x16x32_bf16 v[70:73], v[232:235], v[222:225], v[70:73]
	v_mfma_f32_16x16x32_bf16 v[66:69], v[240:243], v[222:225], v[66:69]
	s_setprio 0
	s_mov_b32 m0, s34
	v_lshl_add_u64 v[250:251], v[244:245], 0, v[138:139]
	s_barrier
	ds_read_b128 v[192:195], v174 offset:16384
	ds_read_b128 v[196:199], v174 offset:17408
	ds_read_b128 v[200:203], v174 offset:18432
	ds_read_b128 v[204:207], v174 offset:19456
	ds_read_b128 v[210:213], v174 offset:20480
	ds_read_b128 v[214:217], v174 offset:21504
	ds_read_b128 v[218:221], v174 offset:22528
	ds_read_b128 v[222:225], v174 offset:23552
	global_load_lds_dwordx4 v[250:251], off
	v_lshl_add_u64 v[252:253], v[244:245], 0, v[148:149]
	s_mov_b32 m0, s41
	s_nop 0
	global_load_lds_dwordx4 v[252:253], off
	s_barrier
	s_setprio 1
	s_waitcnt lgkmcnt(7)
	v_mfma_f32_16x16x32_bf16 v[62:65], v[176:179], v[192:195], v[62:65]
	v_mfma_f32_16x16x32_bf16 v[58:61], v[184:187], v[192:195], v[58:61]
	s_waitcnt lgkmcnt(5)
	v_mfma_f32_16x16x32_bf16 v[54:57], v[176:179], v[200:203], v[54:57]
	v_mfma_f32_16x16x32_bf16 v[50:53], v[184:187], v[200:203], v[50:53]
	s_waitcnt lgkmcnt(3)
	v_mfma_f32_16x16x32_bf16 v[46:49], v[176:179], v[210:213], v[46:49]
	v_mfma_f32_16x16x32_bf16 v[42:45], v[184:187], v[210:213], v[42:45]
	s_waitcnt lgkmcnt(1)
	v_mfma_f32_16x16x32_bf16 v[38:41], v[176:179], v[218:221], v[38:41]
	v_mfma_f32_16x16x32_bf16 v[34:37], v[184:187], v[218:221], v[34:37]
	v_mfma_f32_16x16x32_bf16 v[62:65], v[180:183], v[196:199], v[62:65]
	v_mfma_f32_16x16x32_bf16 v[58:61], v[188:191], v[196:199], v[58:61]
	v_mfma_f32_16x16x32_bf16 v[54:57], v[180:183], v[204:207], v[54:57]
	v_mfma_f32_16x16x32_bf16 v[50:53], v[188:191], v[204:207], v[50:53]
	v_mfma_f32_16x16x32_bf16 v[46:49], v[180:183], v[214:217], v[46:49]
	v_mfma_f32_16x16x32_bf16 v[42:45], v[188:191], v[214:217], v[42:45]
	s_waitcnt lgkmcnt(0)
	v_mfma_f32_16x16x32_bf16 v[38:41], v[180:183], v[222:225], v[38:41]
	v_mfma_f32_16x16x32_bf16 v[34:37], v[188:191], v[222:225], v[34:37]
	s_setprio 0
	s_barrier
	v_lshl_add_u64 v[176:177], v[170:171], 0, s[16:17]
	s_add_i32 s7, s57, s39
	v_lshl_add_u64 v[178:179], v[176:177], 0, v[138:139]
	s_mov_b32 m0, s7
	v_lshl_add_u64 v[176:177], v[176:177], 0, v[148:149]
	global_load_lds_dwordx4 v[178:179], off
	s_add_i32 m0, s7, 0x2000
	s_nop 0
	global_load_lds_dwordx4 v[176:177], off
	s_waitcnt vmcnt(6)
	s_barrier
	s_setprio 1
	v_mfma_f32_16x16x32_bf16 v[30:33], v[228:231], v[192:195], v[30:33]
	v_mfma_f32_16x16x32_bf16 v[26:29], v[236:239], v[192:195], v[26:29]
	v_mfma_f32_16x16x32_bf16 v[22:25], v[228:231], v[200:203], v[22:25]
	v_mfma_f32_16x16x32_bf16 v[18:21], v[236:239], v[200:203], v[18:21]
	v_mfma_f32_16x16x32_bf16 v[14:17], v[228:231], v[210:213], v[14:17]
	v_mfma_f32_16x16x32_bf16 v[10:13], v[236:239], v[210:213], v[10:13]
	v_mfma_f32_16x16x32_bf16 v[6:9], v[228:231], v[218:221], v[6:9]
	v_mfma_f32_16x16x32_bf16 v[2:5], v[236:239], v[218:221], v[2:5]
	v_mfma_f32_16x16x32_bf16 v[30:33], v[232:235], v[196:199], v[30:33]
	v_mfma_f32_16x16x32_bf16 v[26:29], v[240:243], v[196:199], v[26:29]
	v_mfma_f32_16x16x32_bf16 v[22:25], v[232:235], v[204:207], v[22:25]
	v_mfma_f32_16x16x32_bf16 v[18:21], v[240:243], v[204:207], v[18:21]
	v_mfma_f32_16x16x32_bf16 v[14:17], v[232:235], v[214:217], v[14:17]
	v_mfma_f32_16x16x32_bf16 v[10:13], v[240:243], v[214:217], v[10:13]
	v_mfma_f32_16x16x32_bf16 v[6:9], v[232:235], v[222:225], v[6:9]
	v_mfma_f32_16x16x32_bf16 v[2:5], v[240:243], v[222:225], v[2:5]
	s_setprio 0
	s_add_i32 s7, 0, 0x18000
	v_add_u32_e32 v175, s7, v173
	s_barrier
	ds_read_b128 v[176:179], v175
	ds_read_b128 v[180:183], v175 offset:1024
	ds_read_b128 v[184:187], v175 offset:2048
	ds_read_b128 v[188:191], v175 offset:3072
	v_lshl_add_u64 v[228:229], v[244:245], 0, s[16:17]
	s_mov_b32 m0, s42
	v_lshl_add_u64 v[230:231], v[228:229], 0, v[138:139]
	ds_read_b128 v[192:195], v174 offset:32768
	ds_read_b128 v[196:199], v174 offset:33792
	ds_read_b128 v[200:203], v174 offset:34816
	ds_read_b128 v[204:207], v174 offset:35840
	ds_read_b128 v[210:213], v174 offset:36864
	ds_read_b128 v[214:217], v174 offset:37888
	ds_read_b128 v[218:221], v174 offset:38912
	ds_read_b128 v[222:225], v174 offset:39936
	global_load_lds_dwordx4 v[230:231], off
	v_lshl_add_u64 v[228:229], v[228:229], 0, v[148:149]
	s_mov_b32 m0, s43
	s_nop 0
	global_load_lds_dwordx4 v[228:229], off
	s_waitcnt lgkmcnt(8)
	s_barrier
	s_setprio 1
	s_waitcnt lgkmcnt(7)
	v_mfma_f32_16x16x32_bf16 v[126:129], v[176:179], v[192:195], v[126:129]
	v_mfma_f32_16x16x32_bf16 v[122:125], v[184:187], v[192:195], v[122:125]
	s_waitcnt lgkmcnt(5)
	v_mfma_f32_16x16x32_bf16 v[118:121], v[176:179], v[200:203], v[118:121]
	v_mfma_f32_16x16x32_bf16 v[114:117], v[184:187], v[200:203], v[114:117]
	s_waitcnt lgkmcnt(3)
	v_mfma_f32_16x16x32_bf16 v[110:113], v[176:179], v[210:213], v[110:113]
	v_mfma_f32_16x16x32_bf16 v[106:109], v[184:187], v[210:213], v[106:109]
	s_waitcnt lgkmcnt(1)
	v_mfma_f32_16x16x32_bf16 v[102:105], v[176:179], v[218:221], v[102:105]
	v_mfma_f32_16x16x32_bf16 v[98:101], v[184:187], v[218:221], v[98:101]
	v_mfma_f32_16x16x32_bf16 v[126:129], v[180:183], v[196:199], v[126:129]
	v_mfma_f32_16x16x32_bf16 v[122:125], v[188:191], v[196:199], v[122:125]
	v_mfma_f32_16x16x32_bf16 v[118:121], v[180:183], v[204:207], v[118:121]
	v_mfma_f32_16x16x32_bf16 v[114:117], v[188:191], v[204:207], v[114:117]
	v_mfma_f32_16x16x32_bf16 v[110:113], v[180:183], v[214:217], v[110:113]
	v_mfma_f32_16x16x32_bf16 v[106:109], v[188:191], v[214:217], v[106:109]
	s_waitcnt lgkmcnt(0)
	v_mfma_f32_16x16x32_bf16 v[102:105], v[180:183], v[222:225], v[102:105]
	v_mfma_f32_16x16x32_bf16 v[98:101], v[188:191], v[222:225], v[98:101]
	s_setprio 0
	s_barrier
	s_add_i32 s57, 0, 0x1c000
	s_add_i32 s7, s7, s39
	v_add_u32_e32 v175, s57, v173
	v_lshl_add_u64 v[244:245], v[246:247], 0, s[18:19]
	s_mov_b32 m0, s7
	ds_read_b128 v[228:231], v175
	ds_read_b128 v[232:235], v175 offset:1024
	ds_read_b128 v[236:239], v175 offset:2048
	ds_read_b128 v[240:243], v175 offset:3072
	global_load_lds_dwordx4 v[244:245], off
	v_lshl_add_u64 v[244:245], v[248:249], 0, s[18:19]
	s_add_i32 m0, s7, 0x2000
	s_nop 0
	global_load_lds_dwordx4 v[244:245], off
	s_barrier
	s_setprio 1
	s_waitcnt lgkmcnt(3)
	v_mfma_f32_16x16x32_bf16 v[94:97], v[228:231], v[192:195], v[94:97]
	s_waitcnt lgkmcnt(1)
	v_mfma_f32_16x16x32_bf16 v[90:93], v[236:239], v[192:195], v[90:93]
	v_mfma_f32_16x16x32_bf16 v[86:89], v[228:231], v[200:203], v[86:89]
	v_mfma_f32_16x16x32_bf16 v[82:85], v[236:239], v[200:203], v[82:85]
	v_mfma_f32_16x16x32_bf16 v[78:81], v[228:231], v[210:213], v[78:81]
	v_mfma_f32_16x16x32_bf16 v[74:77], v[236:239], v[210:213], v[74:77]
	v_mfma_f32_16x16x32_bf16 v[70:73], v[228:231], v[218:221], v[70:73]
	v_mfma_f32_16x16x32_bf16 v[66:69], v[236:239], v[218:221], v[66:69]
	v_mfma_f32_16x16x32_bf16 v[94:97], v[232:235], v[196:199], v[94:97]
	s_waitcnt lgkmcnt(0)
	v_mfma_f32_16x16x32_bf16 v[90:93], v[240:243], v[196:199], v[90:93]
	v_mfma_f32_16x16x32_bf16 v[86:89], v[232:235], v[204:207], v[86:89]
	v_mfma_f32_16x16x32_bf16 v[82:85], v[240:243], v[204:207], v[82:85]
	v_mfma_f32_16x16x32_bf16 v[78:81], v[232:235], v[214:217], v[78:81]
	v_mfma_f32_16x16x32_bf16 v[74:77], v[240:243], v[214:217], v[74:77]
	v_mfma_f32_16x16x32_bf16 v[70:73], v[232:235], v[222:225], v[70:73]
	v_mfma_f32_16x16x32_bf16 v[66:69], v[240:243], v[222:225], v[66:69]
	s_setprio 0
	s_mov_b32 m0, s55
	v_lshl_add_u64 v[244:245], v[250:251], 0, s[18:19]
	s_barrier
	ds_read_b128 v[192:195], v174 offset:49152
	ds_read_b128 v[196:199], v174 offset:50176
	ds_read_b128 v[200:203], v174 offset:51200
	ds_read_b128 v[204:207], v174 offset:52224
	ds_read_b128 v[210:213], v174 offset:53248
	ds_read_b128 v[214:217], v174 offset:54272
	ds_read_b128 v[218:221], v174 offset:55296
	ds_read_b128 v[222:225], v174 offset:56320
	global_load_lds_dwordx4 v[244:245], off
	v_lshl_add_u64 v[244:245], v[252:253], 0, s[18:19]
	s_mov_b32 m0, s56
	s_nop 0
	global_load_lds_dwordx4 v[244:245], off
	s_barrier
	s_setprio 1
	s_waitcnt lgkmcnt(7)
	v_mfma_f32_16x16x32_bf16 v[62:65], v[176:179], v[192:195], v[62:65]
	v_mfma_f32_16x16x32_bf16 v[58:61], v[184:187], v[192:195], v[58:61]
	s_waitcnt lgkmcnt(5)
	v_mfma_f32_16x16x32_bf16 v[54:57], v[176:179], v[200:203], v[54:57]
	v_mfma_f32_16x16x32_bf16 v[50:53], v[184:187], v[200:203], v[50:53]
	s_waitcnt lgkmcnt(3)
	v_mfma_f32_16x16x32_bf16 v[46:49], v[176:179], v[210:213], v[46:49]
	v_mfma_f32_16x16x32_bf16 v[42:45], v[184:187], v[210:213], v[42:45]
	s_waitcnt lgkmcnt(1)
	v_mfma_f32_16x16x32_bf16 v[38:41], v[176:179], v[218:221], v[38:41]
	v_mfma_f32_16x16x32_bf16 v[34:37], v[184:187], v[218:221], v[34:37]
	v_mfma_f32_16x16x32_bf16 v[62:65], v[180:183], v[196:199], v[62:65]
	v_mfma_f32_16x16x32_bf16 v[58:61], v[188:191], v[196:199], v[58:61]
	v_mfma_f32_16x16x32_bf16 v[54:57], v[180:183], v[204:207], v[54:57]
	v_mfma_f32_16x16x32_bf16 v[50:53], v[188:191], v[204:207], v[50:53]
	v_mfma_f32_16x16x32_bf16 v[46:49], v[180:183], v[214:217], v[46:49]
	v_mfma_f32_16x16x32_bf16 v[42:45], v[188:191], v[214:217], v[42:45]
	s_waitcnt lgkmcnt(0)
	v_mfma_f32_16x16x32_bf16 v[38:41], v[180:183], v[222:225], v[38:41]
	v_mfma_f32_16x16x32_bf16 v[34:37], v[188:191], v[222:225], v[34:37]
	s_setprio 0
	s_barrier
	v_lshl_add_u64 v[170:171], v[170:171], 0, s[20:21]
	s_add_i32 s7, s57, s39
	v_lshl_add_u64 v[176:177], v[170:171], 0, v[138:139]
	s_mov_b32 m0, s7
	v_lshl_add_u64 v[170:171], v[170:171], 0, v[148:149]
	global_load_lds_dwordx4 v[176:177], off
	s_add_i32 m0, s7, 0x2000
	s_nop 0
	global_load_lds_dwordx4 v[170:171], off
	s_waitcnt vmcnt(6)
	s_barrier
	s_setprio 1
	v_mfma_f32_16x16x32_bf16 v[30:33], v[228:231], v[192:195], v[30:33]
	v_mfma_f32_16x16x32_bf16 v[26:29], v[236:239], v[192:195], v[26:29]
	v_mfma_f32_16x16x32_bf16 v[22:25], v[228:231], v[200:203], v[22:25]
	v_mfma_f32_16x16x32_bf16 v[18:21], v[236:239], v[200:203], v[18:21]
	v_mfma_f32_16x16x32_bf16 v[14:17], v[228:231], v[210:213], v[14:17]
	v_mfma_f32_16x16x32_bf16 v[10:13], v[236:239], v[210:213], v[10:13]
	v_mfma_f32_16x16x32_bf16 v[6:9], v[228:231], v[218:221], v[6:9]
	v_mfma_f32_16x16x32_bf16 v[2:5], v[236:239], v[218:221], v[2:5]
	v_mfma_f32_16x16x32_bf16 v[30:33], v[232:235], v[196:199], v[30:33]
	v_mfma_f32_16x16x32_bf16 v[26:29], v[240:243], v[196:199], v[26:29]
	v_mfma_f32_16x16x32_bf16 v[22:25], v[232:235], v[204:207], v[22:25]
	v_mfma_f32_16x16x32_bf16 v[18:21], v[240:243], v[204:207], v[18:21]
	v_mfma_f32_16x16x32_bf16 v[14:17], v[232:235], v[214:217], v[14:17]
	v_mfma_f32_16x16x32_bf16 v[10:13], v[240:243], v[214:217], v[10:13]
	v_mfma_f32_16x16x32_bf16 v[6:9], v[232:235], v[222:225], v[6:9]
	v_mfma_f32_16x16x32_bf16 v[2:5], v[240:243], v[222:225], v[2:5]
	s_setprio 0
	s_add_i32 s6, s6, 2
	s_add_u32 s4, s4, 0x100
	s_addc_u32 s5, s5, 0
	s_cmp_lt_u32 s6, 14
	s_barrier
	s_cbranch_scc1 .LBB0_1788
	s_waitcnt vmcnt(0)
	s_cmpk_gt_u32 s38, 0xff
	s_cbranch_scc1 .LBB0_1791
	s_barrier

.LBB0_1914:
	s_add_u32 s38, s4, 0xf8cd0080
	s_addc_u32 s39, s5, -1
	s_cmp_lg_u32 s37, 40
	s_cselect_b32 s39, s39, 0
	s_cselect_b32 s38, s38, 0
	s_add_i32 s40, 0, 0x10000
	v_add_u32_e32 v156, s40, v162
	ds_read_b128 v[164:167], v156
	ds_read_b128 v[168:171], v156 offset:1024
	ds_read_b128 v[172:175], v156 offset:2048
	ds_read_b128 v[176:179], v156 offset:3072
	v_lshl_add_u64 v[232:233], v[148:149], 0, s[38:39]
	v_lshl_add_u64 v[156:157], v[146:147], 0, s[38:39]
	v_lshl_add_u64 v[214:215], v[150:151], 0, s[4:5]
	s_add_i32 m0, s28, 0xc000
	ds_read_b128 v[180:183], v163
	ds_read_b128 v[184:187], v163 offset:1024
	ds_read_b128 v[188:191], v163 offset:2048
	ds_read_b128 v[192:195], v163 offset:3072
	ds_read_b128 v[196:199], v163 offset:4096
	ds_read_b128 v[200:203], v163 offset:5120
	ds_read_b128 v[204:207], v163 offset:6144
	ds_read_b128 v[210:213], v163 offset:7168
	global_load_lds_dwordx4 v[214:215], off
	v_lshl_add_u64 v[214:215], v[152:153], 0, s[4:5]
	s_add_i32 m0, s28, 0xe000
	s_nop 0
	global_load_lds_dwordx4 v[214:215], off
	s_waitcnt lgkmcnt(8)
	s_barrier
	s_setprio 1
	s_waitcnt lgkmcnt(7)
	v_mfma_f32_16x16x32_bf16 v[126:129], v[164:167], v[180:183], v[126:129]
	v_mfma_f32_16x16x32_bf16 v[122:125], v[172:175], v[180:183], v[122:125]
	s_waitcnt lgkmcnt(5)
	v_mfma_f32_16x16x32_bf16 v[118:121], v[164:167], v[188:191], v[118:121]
	v_mfma_f32_16x16x32_bf16 v[114:117], v[172:175], v[188:191], v[114:117]
	s_waitcnt lgkmcnt(3)
	v_mfma_f32_16x16x32_bf16 v[110:113], v[164:167], v[196:199], v[110:113]
	v_mfma_f32_16x16x32_bf16 v[106:109], v[172:175], v[196:199], v[106:109]
	s_waitcnt lgkmcnt(1)
	v_mfma_f32_16x16x32_bf16 v[102:105], v[164:167], v[204:207], v[102:105]
	v_mfma_f32_16x16x32_bf16 v[98:101], v[172:175], v[204:207], v[98:101]
	v_mfma_f32_16x16x32_bf16 v[126:129], v[168:171], v[184:187], v[126:129]
	v_mfma_f32_16x16x32_bf16 v[122:125], v[176:179], v[184:187], v[122:125]
	v_mfma_f32_16x16x32_bf16 v[118:121], v[168:171], v[192:195], v[118:121]
	v_mfma_f32_16x16x32_bf16 v[114:117], v[176:179], v[192:195], v[114:117]
	v_mfma_f32_16x16x32_bf16 v[110:113], v[168:171], v[200:203], v[110:113]
	v_mfma_f32_16x16x32_bf16 v[106:109], v[176:179], v[200:203], v[106:109]
	s_waitcnt lgkmcnt(0)
	v_mfma_f32_16x16x32_bf16 v[102:105], v[168:171], v[210:213], v[102:105]
	v_mfma_f32_16x16x32_bf16 v[98:101], v[176:179], v[210:213], v[98:101]
	s_setprio 0
	s_barrier
	s_add_i32 s38, 0, 0x14000
	s_add_i32 s39, s40, s27
	v_add_u32_e32 v208, s38, v162
	v_lshl_add_u64 v[234:235], v[156:157], 0, v[130:131]
	s_mov_b32 m0, s39
	ds_read_b128 v[214:217], v208
	ds_read_b128 v[218:221], v208 offset:1024
	ds_read_b128 v[222:225], v208 offset:2048
	ds_read_b128 v[228:231], v208 offset:3072
	global_load_lds_dwordx4 v[234:235], off
	v_lshl_add_u64 v[236:237], v[156:157], 0, v[144:145]
	s_add_i32 m0, s39, 0x2000
	s_nop 0
	global_load_lds_dwordx4 v[236:237], off
	s_barrier
	s_setprio 1
	s_waitcnt lgkmcnt(3)
	v_mfma_f32_16x16x32_bf16 v[94:97], v[214:217], v[180:183], v[94:97]
	s_waitcnt lgkmcnt(1)
	v_mfma_f32_16x16x32_bf16 v[90:93], v[222:225], v[180:183], v[90:93]
	v_mfma_f32_16x16x32_bf16 v[86:89], v[214:217], v[188:191], v[86:89]
	v_mfma_f32_16x16x32_bf16 v[82:85], v[222:225], v[188:191], v[82:85]
	v_mfma_f32_16x16x32_bf16 v[78:81], v[214:217], v[196:199], v[78:81]
	v_mfma_f32_16x16x32_bf16 v[74:77], v[222:225], v[196:199], v[74:77]
	v_mfma_f32_16x16x32_bf16 v[70:73], v[214:217], v[204:207], v[70:73]
	v_mfma_f32_16x16x32_bf16 v[66:69], v[222:225], v[204:207], v[66:69]
	v_mfma_f32_16x16x32_bf16 v[94:97], v[218:221], v[184:187], v[94:97]
	s_waitcnt lgkmcnt(0)
	v_mfma_f32_16x16x32_bf16 v[90:93], v[228:231], v[184:187], v[90:93]
	v_mfma_f32_16x16x32_bf16 v[86:89], v[218:221], v[192:195], v[86:89]
	v_mfma_f32_16x16x32_bf16 v[82:85], v[228:231], v[192:195], v[82:85]
	v_mfma_f32_16x16x32_bf16 v[78:81], v[218:221], v[200:203], v[78:81]
	v_mfma_f32_16x16x32_bf16 v[74:77], v[228:231], v[200:203], v[74:77]
	v_mfma_f32_16x16x32_bf16 v[70:73], v[218:221], v[210:213], v[70:73]
	v_mfma_f32_16x16x32_bf16 v[66:69], v[228:231], v[210:213], v[66:69]
	s_setprio 0
	s_mov_b32 m0, s28
	v_lshl_add_u64 v[238:239], v[232:233], 0, v[130:131]
	s_barrier
	ds_read_b128 v[180:183], v163 offset:16384
	ds_read_b128 v[184:187], v163 offset:17408
	ds_read_b128 v[188:191], v163 offset:18432
	ds_read_b128 v[192:195], v163 offset:19456
	ds_read_b128 v[196:199], v163 offset:20480
	ds_read_b128 v[200:203], v163 offset:21504
	ds_read_b128 v[204:207], v163 offset:22528
	ds_read_b128 v[210:213], v163 offset:23552
	global_load_lds_dwordx4 v[238:239], off
	v_lshl_add_u64 v[240:241], v[232:233], 0, v[144:145]
	s_mov_b32 m0, s29
	s_nop 0
	global_load_lds_dwordx4 v[240:241], off
	s_barrier
	s_setprio 1
	s_waitcnt lgkmcnt(7)
	v_mfma_f32_16x16x32_bf16 v[62:65], v[164:167], v[180:183], v[62:65]
	v_mfma_f32_16x16x32_bf16 v[58:61], v[172:175], v[180:183], v[58:61]
	s_waitcnt lgkmcnt(5)
	v_mfma_f32_16x16x32_bf16 v[54:57], v[164:167], v[188:191], v[54:57]
	v_mfma_f32_16x16x32_bf16 v[50:53], v[172:175], v[188:191], v[50:53]
	s_waitcnt lgkmcnt(3)
	v_mfma_f32_16x16x32_bf16 v[46:49], v[164:167], v[196:199], v[46:49]
	v_mfma_f32_16x16x32_bf16 v[42:45], v[172:175], v[196:199], v[42:45]
	s_waitcnt lgkmcnt(1)
	v_mfma_f32_16x16x32_bf16 v[38:41], v[164:167], v[204:207], v[38:41]
	v_mfma_f32_16x16x32_bf16 v[34:37], v[172:175], v[204:207], v[34:37]
	v_mfma_f32_16x16x32_bf16 v[62:65], v[168:171], v[184:187], v[62:65]
	v_mfma_f32_16x16x32_bf16 v[58:61], v[176:179], v[184:187], v[58:61]
	v_mfma_f32_16x16x32_bf16 v[54:57], v[168:171], v[192:195], v[54:57]
	v_mfma_f32_16x16x32_bf16 v[50:53], v[176:179], v[192:195], v[50:53]
	v_mfma_f32_16x16x32_bf16 v[46:49], v[168:171], v[200:203], v[46:49]
	v_mfma_f32_16x16x32_bf16 v[42:45], v[176:179], v[200:203], v[42:45]
	s_waitcnt lgkmcnt(0)
	v_mfma_f32_16x16x32_bf16 v[38:41], v[168:171], v[210:213], v[38:41]
	v_mfma_f32_16x16x32_bf16 v[34:37], v[176:179], v[210:213], v[34:37]
	s_setprio 0
	s_barrier
	v_lshl_add_u64 v[164:165], v[156:157], 0, s[16:17]
	s_add_i32 s38, s38, s27
	v_lshl_add_u64 v[166:167], v[164:165], 0, v[130:131]
	s_mov_b32 m0, s38
	v_lshl_add_u64 v[164:165], v[164:165], 0, v[144:145]
	global_load_lds_dwordx4 v[166:167], off
	s_add_i32 m0, s38, 0x2000
	s_nop 0
	global_load_lds_dwordx4 v[164:165], off
	s_waitcnt vmcnt(6)
	s_barrier
	s_setprio 1
	v_mfma_f32_16x16x32_bf16 v[30:33], v[214:217], v[180:183], v[30:33]
	v_mfma_f32_16x16x32_bf16 v[26:29], v[222:225], v[180:183], v[26:29]
	v_mfma_f32_16x16x32_bf16 v[22:25], v[214:217], v[188:191], v[22:25]
	v_mfma_f32_16x16x32_bf16 v[18:21], v[222:225], v[188:191], v[18:21]
	v_mfma_f32_16x16x32_bf16 v[14:17], v[214:217], v[196:199], v[14:17]
	v_mfma_f32_16x16x32_bf16 v[10:13], v[222:225], v[196:199], v[10:13]
	v_mfma_f32_16x16x32_bf16 v[6:9], v[214:217], v[204:207], v[6:9]
	v_mfma_f32_16x16x32_bf16 v[2:5], v[222:225], v[204:207], v[2:5]
	v_mfma_f32_16x16x32_bf16 v[30:33], v[218:221], v[184:187], v[30:33]
	v_mfma_f32_16x16x32_bf16 v[26:29], v[228:231], v[184:187], v[26:29]
	v_mfma_f32_16x16x32_bf16 v[22:25], v[218:221], v[192:195], v[22:25]
	v_mfma_f32_16x16x32_bf16 v[18:21], v[228:231], v[192:195], v[18:21]
	v_mfma_f32_16x16x32_bf16 v[14:17], v[218:221], v[200:203], v[14:17]
	v_mfma_f32_16x16x32_bf16 v[10:13], v[228:231], v[200:203], v[10:13]
	v_mfma_f32_16x16x32_bf16 v[6:9], v[218:221], v[210:213], v[6:9]
	v_mfma_f32_16x16x32_bf16 v[2:5], v[228:231], v[210:213], v[2:5]
	s_setprio 0
	s_add_i32 s38, 0, 0x18000
	v_add_u32_e32 v176, s38, v162
	s_barrier
	ds_read_b128 v[164:167], v176
	ds_read_b128 v[168:171], v176 offset:1024
	ds_read_b128 v[172:175], v176 offset:2048
	ds_read_b128 v[176:179], v176 offset:3072
	v_lshl_add_u64 v[214:215], v[232:233], 0, s[16:17]
	s_mov_b32 m0, s31
	v_lshl_add_u64 v[216:217], v[214:215], 0, v[130:131]
	ds_read_b128 v[180:183], v163 offset:32768
	ds_read_b128 v[184:187], v163 offset:33792
	ds_read_b128 v[188:191], v163 offset:34816
	ds_read_b128 v[192:195], v163 offset:35840
	ds_read_b128 v[196:199], v163 offset:36864
	ds_read_b128 v[200:203], v163 offset:37888
	ds_read_b128 v[204:207], v163 offset:38912
	ds_read_b128 v[210:213], v163 offset:39936
	global_load_lds_dwordx4 v[216:217], off
	v_lshl_add_u64 v[214:215], v[214:215], 0, v[144:145]
	s_mov_b32 m0, s34
	s_nop 0
	global_load_lds_dwordx4 v[214:215], off
	s_waitcnt lgkmcnt(8)
	s_barrier
	s_setprio 1
	s_waitcnt lgkmcnt(7)
	v_mfma_f32_16x16x32_bf16 v[126:129], v[164:167], v[180:183], v[126:129]
	v_mfma_f32_16x16x32_bf16 v[122:125], v[172:175], v[180:183], v[122:125]
	s_waitcnt lgkmcnt(5)
	v_mfma_f32_16x16x32_bf16 v[118:121], v[164:167], v[188:191], v[118:121]
	v_mfma_f32_16x16x32_bf16 v[114:117], v[172:175], v[188:191], v[114:117]
	s_waitcnt lgkmcnt(3)
	v_mfma_f32_16x16x32_bf16 v[110:113], v[164:167], v[196:199], v[110:113]
	v_mfma_f32_16x16x32_bf16 v[106:109], v[172:175], v[196:199], v[106:109]
	s_waitcnt lgkmcnt(1)
	v_mfma_f32_16x16x32_bf16 v[102:105], v[164:167], v[204:207], v[102:105]
	v_mfma_f32_16x16x32_bf16 v[98:101], v[172:175], v[204:207], v[98:101]
	v_mfma_f32_16x16x32_bf16 v[126:129], v[168:171], v[184:187], v[126:129]
	v_mfma_f32_16x16x32_bf16 v[122:125], v[176:179], v[184:187], v[122:125]
	v_mfma_f32_16x16x32_bf16 v[118:121], v[168:171], v[192:195], v[118:121]
	v_mfma_f32_16x16x32_bf16 v[114:117], v[176:179], v[192:195], v[114:117]
	v_mfma_f32_16x16x32_bf16 v[110:113], v[168:171], v[200:203], v[110:113]
	v_mfma_f32_16x16x32_bf16 v[106:109], v[176:179], v[200:203], v[106:109]
	s_waitcnt lgkmcnt(0)
	v_mfma_f32_16x16x32_bf16 v[102:105], v[168:171], v[210:213], v[102:105]
	v_mfma_f32_16x16x32_bf16 v[98:101], v[176:179], v[210:213], v[98:101]
	s_setprio 0
	s_barrier
	s_add_i32 s39, 0, 0x1c000
	s_add_i32 s38, s38, s27
	v_add_u32_e32 v208, s39, v162
	v_lshl_add_u64 v[232:233], v[234:235], 0, s[18:19]
	s_mov_b32 m0, s38
	ds_read_b128 v[214:217], v208
	ds_read_b128 v[218:221], v208 offset:1024
	ds_read_b128 v[222:225], v208 offset:2048
	ds_read_b128 v[228:231], v208 offset:3072
	global_load_lds_dwordx4 v[232:233], off
	v_lshl_add_u64 v[232:233], v[236:237], 0, s[18:19]
	s_add_i32 m0, s38, 0x2000
	s_nop 0
	global_load_lds_dwordx4 v[232:233], off
	s_barrier
	s_setprio 1
	s_waitcnt lgkmcnt(3)
	v_mfma_f32_16x16x32_bf16 v[94:97], v[214:217], v[180:183], v[94:97]
	s_waitcnt lgkmcnt(1)
	v_mfma_f32_16x16x32_bf16 v[90:93], v[222:225], v[180:183], v[90:93]
	v_mfma_f32_16x16x32_bf16 v[86:89], v[214:217], v[188:191], v[86:89]
	v_mfma_f32_16x16x32_bf16 v[82:85], v[222:225], v[188:191], v[82:85]
	v_mfma_f32_16x16x32_bf16 v[78:81], v[214:217], v[196:199], v[78:81]
	v_mfma_f32_16x16x32_bf16 v[74:77], v[222:225], v[196:199], v[74:77]
	v_mfma_f32_16x16x32_bf16 v[70:73], v[214:217], v[204:207], v[70:73]
	v_mfma_f32_16x16x32_bf16 v[66:69], v[222:225], v[204:207], v[66:69]
	v_mfma_f32_16x16x32_bf16 v[94:97], v[218:221], v[184:187], v[94:97]
	s_waitcnt lgkmcnt(0)
	v_mfma_f32_16x16x32_bf16 v[90:93], v[228:231], v[184:187], v[90:93]
	v_mfma_f32_16x16x32_bf16 v[86:89], v[218:221], v[192:195], v[86:89]
	v_mfma_f32_16x16x32_bf16 v[82:85], v[228:231], v[192:195], v[82:85]
	v_mfma_f32_16x16x32_bf16 v[78:81], v[218:221], v[200:203], v[78:81]
	v_mfma_f32_16x16x32_bf16 v[74:77], v[228:231], v[200:203], v[74:77]
	v_mfma_f32_16x16x32_bf16 v[70:73], v[218:221], v[210:213], v[70:73]
	v_mfma_f32_16x16x32_bf16 v[66:69], v[228:231], v[210:213], v[66:69]
	s_setprio 0
	s_mov_b32 m0, s35
	v_lshl_add_u64 v[232:233], v[238:239], 0, s[18:19]
	s_barrier
	ds_read_b128 v[180:183], v163 offset:49152
	ds_read_b128 v[184:187], v163 offset:50176
	ds_read_b128 v[188:191], v163 offset:51200
	ds_read_b128 v[192:195], v163 offset:52224
	ds_read_b128 v[196:199], v163 offset:53248
	ds_read_b128 v[200:203], v163 offset:54272
	ds_read_b128 v[204:207], v163 offset:55296
	ds_read_b128 v[210:213], v163 offset:56320
	global_load_lds_dwordx4 v[232:233], off
	v_lshl_add_u64 v[232:233], v[240:241], 0, s[18:19]
	s_mov_b32 m0, s36
	s_nop 0
	global_load_lds_dwordx4 v[232:233], off
	s_barrier
	s_setprio 1
	s_waitcnt lgkmcnt(7)
	v_mfma_f32_16x16x32_bf16 v[62:65], v[164:167], v[180:183], v[62:65]
	v_mfma_f32_16x16x32_bf16 v[58:61], v[172:175], v[180:183], v[58:61]
	s_waitcnt lgkmcnt(5)
	v_mfma_f32_16x16x32_bf16 v[54:57], v[164:167], v[188:191], v[54:57]
	v_mfma_f32_16x16x32_bf16 v[50:53], v[172:175], v[188:191], v[50:53]
	s_waitcnt lgkmcnt(3)
	v_mfma_f32_16x16x32_bf16 v[46:49], v[164:167], v[196:199], v[46:49]
	v_mfma_f32_16x16x32_bf16 v[42:45], v[172:175], v[196:199], v[42:45]
	s_waitcnt lgkmcnt(1)
	v_mfma_f32_16x16x32_bf16 v[38:41], v[164:167], v[204:207], v[38:41]
	v_mfma_f32_16x16x32_bf16 v[34:37], v[172:175], v[204:207], v[34:37]
	v_mfma_f32_16x16x32_bf16 v[62:65], v[168:171], v[184:187], v[62:65]
	v_mfma_f32_16x16x32_bf16 v[58:61], v[176:179], v[184:187], v[58:61]
	v_mfma_f32_16x16x32_bf16 v[54:57], v[168:171], v[192:195], v[54:57]
	v_mfma_f32_16x16x32_bf16 v[50:53], v[176:179], v[192:195], v[50:53]
	v_mfma_f32_16x16x32_bf16 v[46:49], v[168:171], v[200:203], v[46:49]
	v_mfma_f32_16x16x32_bf16 v[42:45], v[176:179], v[200:203], v[42:45]
	s_waitcnt lgkmcnt(0)
	v_mfma_f32_16x16x32_bf16 v[38:41], v[168:171], v[210:213], v[38:41]
	v_mfma_f32_16x16x32_bf16 v[34:37], v[176:179], v[210:213], v[34:37]
	s_setprio 0
	s_barrier
	v_lshl_add_u64 v[156:157], v[156:157], 0, s[20:21]
	s_add_i32 s38, s39, s27
	v_lshl_add_u64 v[164:165], v[156:157], 0, v[130:131]
	s_mov_b32 m0, s38
	v_lshl_add_u64 v[156:157], v[156:157], 0, v[144:145]
	global_load_lds_dwordx4 v[164:165], off
	s_add_i32 m0, s38, 0x2000
	s_nop 0
	global_load_lds_dwordx4 v[156:157], off
	s_waitcnt vmcnt(6)
	s_barrier
	s_setprio 1
	v_mfma_f32_16x16x32_bf16 v[30:33], v[214:217], v[180:183], v[30:33]
	v_mfma_f32_16x16x32_bf16 v[26:29], v[222:225], v[180:183], v[26:29]
	v_mfma_f32_16x16x32_bf16 v[22:25], v[214:217], v[188:191], v[22:25]
	v_mfma_f32_16x16x32_bf16 v[18:21], v[222:225], v[188:191], v[18:21]
	v_mfma_f32_16x16x32_bf16 v[14:17], v[214:217], v[196:199], v[14:17]
	v_mfma_f32_16x16x32_bf16 v[10:13], v[222:225], v[196:199], v[10:13]
	v_mfma_f32_16x16x32_bf16 v[6:9], v[214:217], v[204:207], v[6:9]
	v_mfma_f32_16x16x32_bf16 v[2:5], v[222:225], v[204:207], v[2:5]
	v_mfma_f32_16x16x32_bf16 v[30:33], v[218:221], v[184:187], v[30:33]
	v_mfma_f32_16x16x32_bf16 v[26:29], v[228:231], v[184:187], v[26:29]
	v_mfma_f32_16x16x32_bf16 v[22:25], v[218:221], v[192:195], v[22:25]
	v_mfma_f32_16x16x32_bf16 v[18:21], v[228:231], v[192:195], v[18:21]
	v_mfma_f32_16x16x32_bf16 v[14:17], v[218:221], v[200:203], v[14:17]
	v_mfma_f32_16x16x32_bf16 v[10:13], v[228:231], v[200:203], v[10:13]
	v_mfma_f32_16x16x32_bf16 v[6:9], v[218:221], v[210:213], v[6:9]
	v_mfma_f32_16x16x32_bf16 v[2:5], v[228:231], v[210:213], v[2:5]
	s_setprio 0
	s_add_i32 s37, s37, 2
	s_add_u32 s4, s4, 0x100
	s_addc_u32 s5, s5, 0
	s_cmp_lt_u32 s37, 42
	s_barrier
	s_cbranch_scc1 .LBB0_1914
	s_waitcnt vmcnt(0)
	s_cmpk_gt_u32 s26, 0xff
	s_cbranch_scc1 .LBB0_1917
	s_barrier
